# v113 + GLU weights, D-skip and GLU biases also loaded at the start of the S5 carry phase (only A_bar/B_bar/A16/A256 are fetched before pass 1)
# baseline (speedup 1.0000x reference)
; #define LAS __attribute__((address_space(3)))
; __device__ __forceinline__ bf16x8 pack8(f32x4 lo, f32x4 hi) { v4u w; w.x = pk2(lo[0], lo[1]); w.y = pk2(lo[2], lo[3]); w.z = pk2(hi[0], hi[1]); w.w = pk2(hi[2], hi[3]); return __builtin_bit_cast(bf16x8, w); }
; __device__ __forceinline__ void gmlp_compute(GmlpRegs& R, const Args& a, const Ctx& C, int c, int hd) {
;     ...
;     const float lg = R.lg, lb = R.lb;
;     bf16x8 af[4];
; #pragma unroll
;     for (int ks = 0; ks < 4; ++ks) { f32x4 lo, hi;
; #pragma unroll
;         for (int e = 0; e < 8; ++e) { const int sl = 32 * ks + 8 * q + e;
;             const float v = __uint_as_float((unsigned)*(const LAS unsigned short*)(VL + sl * 260 + (16 * w + fr) * 2) << 16);
;             const float x = (v - ST[2 * sl]) * ST[2 * sl + 1] * lg + lb; if (e < 4) lo[e] = x; else hi[e - 4] = x; }
;         af[ks] = pack8(lo, hi); }
.LBB0_973:
	s_or_b64 exec, exec, s[4:5]
	s_waitcnt lgkmcnt(0)
	s_barrier
	v_add_u32_e32 v18, v165, v184
	ds_read_b128 v[2:5], v183
	ds_read_u16 v6, v18 offset:34816
	ds_read_u16 v7, v18 offset:35076
	ds_read_u16 v14, v18 offset:35596
	ds_read_u16 v15, v18 offset:36116
	ds_read_u16 v19, v18 offset:36636
	ds_read_u16 v20, v18 offset:43396
	ds_read_u16 v21, v18 offset:43916
	ds_read_u16 v22, v18 offset:44436
	s_waitcnt lgkmcnt(6)
	v_lshlrev_b32_e32 v11, 16, v7
	v_lshlrev_b32_e32 v10, 16, v6
	ds_read_b128 v[6:9], v168
	v_mov_b32_e32 v12, v2
	v_mov_b32_e32 v13, v4
	v_pk_add_f32 v[10:11], v[10:11], v[12:13] neg_lo:[0,1] neg_hi:[0,1]
	v_mov_b32_e32 v4, v3
	v_pk_mul_f32 v[2:3], v[4:5], v[10:11]
	s_waitcnt lgkmcnt(0)
	v_mov_b32_e32 v5, v8
	v_pk_fma_f32 v[10:11], v[98:99], v[2:3], v[100:101]
	v_add_u32_e32 v2, v165, v167
	v_lshlrev_b32_e32 v3, 16, v14
	ds_read_u16 v4, v2 offset:34816
	ds_read_u16 v14, v2 offset:35336
	ds_read_u16 v23, v2 offset:35856
	ds_read_u16 v24, v2 offset:42616
	ds_read_u16 v25, v2 offset:43136
	ds_read_u16 v113, v18 offset:61596
	s_waitcnt lgkmcnt(5)
	v_lshlrev_b32_e32 v2, 16, v4
	v_mov_b32_e32 v4, v6
	v_pk_add_f32 v[2:3], v[2:3], v[4:5] neg_lo:[0,1] neg_hi:[0,1]
	v_mov_b32_e32 v8, v7
	v_pk_mul_f32 v[6:7], v[8:9], v[2:3]
	ds_read_b128 v[2:5], v163
	v_pk_fma_f32 v[12:13], v[98:99], v[6:7], v[100:101]
	ds_read_b128 v[6:9], v166
	v_lshlrev_b32_e32 v15, 16, v15
	s_waitcnt lgkmcnt(6)
	v_lshlrev_b32_e32 v14, 16, v14
	s_waitcnt lgkmcnt(1)
	v_mov_b32_e32 v16, v2
	v_mov_b32_e32 v17, v4
	v_pk_add_f32 v[14:15], v[14:15], v[16:17] neg_lo:[0,1] neg_hi:[0,1]
	v_mov_b32_e32 v4, v3
	v_pk_mul_f32 v[2:3], v[4:5], v[14:15]
	s_waitcnt lgkmcnt(0)
	v_mov_b32_e32 v14, v6
	v_pk_fma_f32 v[4:5], v[98:99], v[2:3], v[100:101]
	v_lshlrev_b32_e32 v3, 16, v19
	v_lshlrev_b32_e32 v2, 16, v23
	v_mov_b32_e32 v15, v8
	v_pk_add_f32 v[2:3], v[2:3], v[14:15] neg_lo:[0,1] neg_hi:[0,1]
	v_mov_b32_e32 v8, v7
	v_pk_mul_f32 v[2:3], v[8:9], v[2:3]
	ds_read_b128 v[6:9], v185
	v_pk_fma_f32 v[14:15], v[98:99], v[2:3], v[100:101]
	v_cvt_pk_bf16_f32 v2, v10, v11
	v_cvt_pk_bf16_f32 v3, v12, v13
	ds_read_b128 v[10:13], v186
	v_cvt_pk_bf16_f32 v4, v4, v5
	v_cvt_pk_bf16_f32 v5, v14, v15
	v_lshlrev_b32_e32 v15, 16, v20
	v_lshlrev_b32_e32 v14, 16, v24
	s_waitcnt lgkmcnt(1)
	v_mov_b32_e32 v16, v6
	v_mov_b32_e32 v17, v8
	v_pk_add_f32 v[14:15], v[14:15], v[16:17] neg_lo:[0,1] neg_hi:[0,1]
	v_mov_b32_e32 v8, v7
	v_pk_mul_f32 v[6:7], v[8:9], v[14:15]
	s_waitcnt lgkmcnt(0)
	v_mov_b32_e32 v8, v10
	v_pk_fma_f32 v[14:15], v[98:99], v[6:7], v[100:101]
	v_lshlrev_b32_e32 v7, 16, v21
	v_lshlrev_b32_e32 v6, 16, v25
	v_mov_b32_e32 v9, v12
	v_pk_add_f32 v[16:17], v[6:7], v[8:9] neg_lo:[0,1] neg_hi:[0,1]
	ds_read_u16 v19, v187 offset:34816
	ds_read_u16 v20, v187 offset:35336
	ds_read_u16 v21, v187 offset:42096
	ds_read_b128 v[6:9], v188
	v_mov_b32_e32 v12, v11
	v_pk_mul_f32 v[10:11], v[12:13], v[16:17]
	v_lshlrev_b32_e32 v13, 16, v22
	s_waitcnt lgkmcnt(3)
	v_lshlrev_b32_e32 v12, 16, v19
	s_waitcnt lgkmcnt(0)
	v_mov_b32_e32 v16, v6
	v_mov_b32_e32 v17, v8
	v_pk_add_f32 v[12:13], v[12:13], v[16:17] neg_lo:[0,1] neg_hi:[0,1]
	v_mov_b32_e32 v8, v7
	v_pk_mul_f32 v[6:7], v[8:9], v[12:13]
	v_pk_fma_f32 v[10:11], v[98:99], v[10:11], v[100:101]
	v_pk_fma_f32 v[12:13], v[98:99], v[6:7], v[100:101]
	ds_read_b128 v[6:9], v189
	ds_read_u16 v16, v18 offset:44956
	ds_read_u16 v22, v18 offset:51716
	ds_read_u16 v23, v18 offset:52236
	ds_read_u16 v24, v18 offset:52756
	ds_read_u16 v26, v18 offset:53276
	ds_read_u16 v27, v18 offset:60036
	ds_read_u16 v28, v18 offset:60556
	ds_read_u16 v36, v18 offset:61076
	s_waitcnt lgkmcnt(7)
	v_lshlrev_b32_e32 v17, 16, v16
	v_lshlrev_b32_e32 v16, 16, v20
	v_mov_b32_e32 v18, v6
	v_mov_b32_e32 v19, v8
	v_pk_add_f32 v[16:17], v[16:17], v[18:19] neg_lo:[0,1] neg_hi:[0,1]
	v_mov_b32_e32 v8, v7
	v_pk_mul_f32 v[6:7], v[8:9], v[16:17]
	ds_read_u16 v25, v187 offset:42616
	ds_read_u16 v29, v187 offset:43136
	v_pk_fma_f32 v[16:17], v[98:99], v[6:7], v[100:101]
	v_cvt_pk_bf16_f32 v7, v10, v11
	v_cvt_pk_bf16_f32 v8, v12, v13
	ds_read_b128 v[10:13], v190
	v_cvt_pk_bf16_f32 v6, v14, v15
	v_cvt_pk_bf16_f32 v9, v16, v17
	ds_read_b128 v[14:17], v191
	s_waitcnt lgkmcnt(10)
	v_lshlrev_b32_e32 v19, 16, v22
	v_lshlrev_b32_e32 v18, 16, v21
	s_waitcnt lgkmcnt(1)
	v_mov_b32_e32 v20, v10
	v_mov_b32_e32 v21, v12
	v_pk_add_f32 v[18:19], v[18:19], v[20:21] neg_lo:[0,1] neg_hi:[0,1]
	v_mov_b32_e32 v12, v11
	v_pk_mul_f32 v[10:11], v[12:13], v[18:19]
	s_waitcnt lgkmcnt(0)
	v_mov_b32_e32 v12, v14
	v_pk_fma_f32 v[18:19], v[98:99], v[10:11], v[100:101]
	v_lshlrev_b32_e32 v11, 16, v23
	v_lshlrev_b32_e32 v10, 16, v25
	v_mov_b32_e32 v13, v16
	v_pk_add_f32 v[10:11], v[10:11], v[12:13] neg_lo:[0,1] neg_hi:[0,1]
	v_mov_b32_e32 v16, v15
	v_pk_mul_f32 v[14:15], v[16:17], v[10:11]
	ds_read_b128 v[10:13], v192
	v_pk_fma_f32 v[20:21], v[98:99], v[14:15], v[100:101]
	ds_read_b128 v[14:17], v194
	v_lshlrev_b32_e32 v23, 16, v24
	v_lshlrev_b32_e32 v22, 16, v29
	s_waitcnt lgkmcnt(1)
	v_mov_b32_e32 v24, v10
	v_mov_b32_e32 v25, v12
	v_pk_add_f32 v[22:23], v[22:23], v[24:25] neg_lo:[0,1] neg_hi:[0,1]
	v_mov_b32_e32 v12, v11
	v_pk_mul_f32 v[10:11], v[12:13], v[22:23]
	s_waitcnt lgkmcnt(0)
	v_mov_b32_e32 v22, v14
	v_pk_fma_f32 v[12:13], v[98:99], v[10:11], v[100:101]
	ds_read_u16 v10, v193 offset:34816
	ds_read_u16 v24, v193 offset:41576
	ds_read_u16 v29, v193 offset:42096
	ds_read_u16 v38, v193 offset:42616
	ds_read_u16 v121, v193 offset:43136
	v_lshlrev_b32_e32 v11, 16, v26
	s_waitcnt lgkmcnt(4)
; #define LAS __attribute__((address_space(3)))
; #define MFMA16(A, B, Cc) __builtin_amdgcn_mfma_f32_16x16x32_bf16((A), (B), (Cc), 0, 0, 0)
; #define PIN(x) asm volatile("" : "+v"(x))
; __device__ __forceinline__ float bf_lo(unsigned w) { return __uint_as_float(w << 16); }
; __device__ __forceinline__ unsigned pk4f8(float a, float b, float c, float d) { int p = __builtin_amdgcn_cvt_pk_fp8_f32(sat8(a), sat8(b), 0, false); p = __builtin_amdgcn_cvt_pk_fp8_f32(sat8(c), sat8(d), p, true); return (unsigned)p; }
; __device__ __forceinline__ float bf_hi(unsigned w) { return __uint_as_float(w & 0xffff0000u); }
; __device__ __forceinline__ bf16x8 pack8(f32x4 lo, f32x4 hi) { v4u w; w.x = pk2(lo[0], lo[1]); w.y = pk2(lo[2], lo[3]); w.z = pk2(hi[0], hi[1]); w.w = pk2(hi[2], hi[3]); return __builtin_bit_cast(bf16x8, w); }
; __device__ __forceinline__ void gmlp_compute(GmlpRegs& R, const Args& a, const Ctx& C, int c, int hd) {
;     ...
;     for (int ks = 0; ks < 4; ++ks) { f32x4 lo, hi;
; #pragma unroll
;         for (int e = 0; e < 8; ++e) { const int sl = 32 * ks + 8 * q + e;
;             const float v = __uint_as_float((unsigned)*(const LAS unsigned short*)(VL + sl * 260 + (16 * w + fr) * 2) << 16);
;             const float x = (v - ST[2 * sl]) * ST[2 * sl + 1] * lg + lb; if (e < 4) lo[e] = x; else hi[e - 4] = x; }
;         af[ks] = pack8(lo, hi); }
;     f32x4 acc[8];
; #pragma unroll
;     for (int nt = 0; nt < 8; ++nt) { acc[nt] = (f32x4){0.f, 0.f, 0.f, 0.f};
; #pragma unroll
;         for (int ks = 0; ks <= nt / 2; ++ks) acc[nt] = MFMA16(af[ks], *(const LAS bf16x8*)(WL + (16 * nt + fr) * 272 + (32 * ks + 8 * q) * 2), acc[nt]); }
; #pragma unroll
;     for (int nt = 0; nt < 8; ++nt) PIN(R.uq[nt]);
; #pragma unroll
;     for (int nt = 0; nt < 8; ++nt) { const size_t row = T0 + 16 * nt + fr; const float bs = R.bsv[nt];
;         const float o0 = bf_lo(R.uq[nt].x) * (acc[nt][0] + bs), o1 = bf_hi(R.uq[nt].x) * (acc[nt][1] + bs);
;         const float o2 = bf_lo(R.uq[nt].y) * (acc[nt][2] + bs), o3 = bf_hi(R.uq[nt].y) * (acc[nt][3] + bs);
;         *(unsigned*)((unsigned char*)Y + row * DM + chs) = pk4f8(o0, o1, o2, o3); }
	v_lshlrev_b32_e32 v10, 16, v10
	v_mov_b32_e32 v23, v16
	v_pk_add_f32 v[10:11], v[10:11], v[22:23] neg_lo:[0,1] neg_hi:[0,1]
	v_mov_b32_e32 v16, v15
	v_pk_mul_f32 v[10:11], v[16:17], v[10:11]
	ds_read_b128 v[14:17], v195
	v_pk_fma_f32 v[22:23], v[98:99], v[10:11], v[100:101]
	v_cvt_pk_bf16_f32 v10, v18, v19
	v_cvt_pk_bf16_f32 v11, v20, v21
	v_cvt_pk_bf16_f32 v12, v12, v13
	v_cvt_pk_bf16_f32 v13, v22, v23
	v_lshlrev_b32_e32 v23, 16, v27
	s_waitcnt lgkmcnt(4)
	v_lshlrev_b32_e32 v22, 16, v24
	ds_read_b128 v[18:21], v196
	s_waitcnt lgkmcnt(1)
	v_mov_b32_e32 v24, v14
	v_mov_b32_e32 v25, v16
	v_pk_add_f32 v[26:27], v[22:23], v[24:25] neg_lo:[0,1] neg_hi:[0,1]
	v_mov_b32_e32 v16, v15
	v_add_u32_e32 v126, v199, v200
	v_pk_mul_f32 v[14:15], v[16:17], v[26:27]
	v_lshlrev_b32_e32 v31, 16, v28
	v_lshlrev_b32_e32 v30, 16, v29
	ds_read_b128 v[26:29], v126 offset:8704
	s_waitcnt lgkmcnt(1)
	v_mov_b32_e32 v32, v18
	v_mov_b32_e32 v33, v20
	v_pk_add_f32 v[34:35], v[30:31], v[32:33] neg_lo:[0,1] neg_hi:[0,1]
	ds_read_b128 v[30:33], v126 offset:8768
	v_mov_b32_e32 v20, v19
	s_waitcnt lgkmcnt(1)
	v_mfma_f32_16x16x32_bf16 v[26:29], v[2:5], v[26:29], 0
	v_mul_f32_e64 v34, v20, v34
	v_mul_f32_e64 v35, v21, v35
	ds_read_b128 v[18:21], v126 offset:13056
	v_lshlrev_b32_e32 v46, 16, v38
	ds_read_b128 v[38:41], v126 offset:17408
	ds_read_b128 v[42:45], v126 offset:17472
	s_waitcnt lgkmcnt(3)
	v_mfma_f32_16x16x32_bf16 v[26:29], v[6:9], v[30:33], v[26:29]
	v_fma_f32 v92, v98, v34, v100
	v_fma_f32 v93, v99, v35, v101
	v_lshlrev_b32_e32 v47, 16, v36
	ds_read_b128 v[30:33], v126 offset:13120
	ds_read_b128 v[34:37], v197
	s_waitcnt lgkmcnt(4)
	v_mfma_f32_16x16x32_bf16 v[18:21], v[2:5], v[18:21], 0
	v_fma_f32 v88, v98, v14, v100
	v_fma_f32 v89, v99, v15, v101
	ds_read_b128 v[22:25], v126
	ds_read_b128 v[14:17], v126 offset:4352
	s_waitcnt lgkmcnt(5)
	v_mfma_f32_16x16x32_bf16 v[38:41], v[2:5], v[38:41], 0
	s_lshl_b64 s[4:5], s[70:71], 11
	s_mov_b64 s[8:9], 0x2300000
	v_readlane_b32 s16, v249, 1
	s_waitcnt lgkmcnt(3)
	v_mfma_f32_16x16x32_bf16 v[18:21], v[6:9], v[30:33], v[18:21]
	ds_read_b128 v[30:33], v198
	s_waitcnt lgkmcnt(3)
	v_mov_b32_e32 v48, v34
	v_mov_b32_e32 v49, v36
	v_pk_add_f32 v[90:91], v[46:47], v[48:49] neg_lo:[0,1] neg_hi:[0,1]
	v_mov_b32_e32 v36, v35
	ds_read_b128 v[46:49], v126 offset:17536
	v_mfma_f32_16x16x32_bf16 v[38:41], v[6:9], v[42:45], v[38:41]
	v_mul_f32_e64 v42, v36, v90
	v_mul_f32_e64 v43, v37, v91
	ds_read_b128 v[34:37], v126 offset:21760
	v_pk_fma_f32 v[122:123], v[98:99], v[42:43], v[100:101]
	ds_read_b128 v[42:45], v126 offset:21824
	s_waitcnt lgkmcnt(1)
	v_mfma_f32_16x16x32_bf16 v[34:37], v[2:5], v[34:37], 0
	v_lshlrev_b32_e32 v91, 16, v113
	v_lshlrev_b32_e32 v90, 16, v121
	v_mov_b32_e32 v124, v30
	v_mfma_f32_16x16x32_bf16 v[38:41], v[10:13], v[46:49], v[38:41]
	ds_read_b128 v[46:49], v126 offset:21888
	v_mov_b32_e32 v125, v32
	v_pk_add_f32 v[90:91], v[90:91], v[124:125] neg_lo:[0,1] neg_hi:[0,1]
	s_waitcnt lgkmcnt(1)
	v_mfma_f32_16x16x32_bf16 v[34:37], v[6:9], v[42:45], v[34:37]
	ds_read_b128 v[42:45], v126 offset:26112
	v_mov_b32_e32 v32, v31
	v_readlane_b32 s17, v249, 2
	s_waitcnt lgkmcnt(1)
	v_mfma_f32_16x16x32_bf16 v[34:37], v[10:13], v[46:49], v[34:37]
	v_mul_f32_e64 v46, v32, v90
	v_mul_f32_e64 v47, v33, v91
	ds_read_b128 v[30:33], v126 offset:26176
	v_pk_fma_f32 v[98:99], v[98:99], v[46:47], v[100:101]
	s_waitcnt lgkmcnt(1)
	v_mfma_f32_16x16x32_bf16 v[42:45], v[2:5], v[42:45], 0
	v_cvt_pk_bf16_f32 v46, v88, v89
	ds_read_b128 v[88:91], v126 offset:26240
	v_cvt_pk_bf16_f32 v47, v92, v93
	s_waitcnt lgkmcnt(1)
	v_mfma_f32_16x16x32_bf16 v[30:33], v[6:9], v[30:33], v[42:45]
	v_cvt_pk_bf16_f32 v48, v122, v123
	v_cvt_pk_bf16_f32 v49, v98, v99
	v_readlane_b32 s18, v249, 3
	ds_read_b128 v[42:45], v126 offset:26304
	s_waitcnt lgkmcnt(1)
	v_mfma_f32_16x16x32_bf16 v[30:33], v[10:13], v[88:91], v[30:33]
	v_readlane_b32 s19, v249, 4
	v_readlane_b32 s20, v249, 5
	v_readlane_b32 s21, v249, 6
	s_waitcnt lgkmcnt(0)
	v_mfma_f32_16x16x32_bf16 v[30:33], v[46:49], v[42:45], v[30:33]
	ds_read_b128 v[42:45], v126 offset:30464
	ds_read_b128 v[88:91], v126 offset:30528
	v_readlane_b32 s22, v249, 7
	v_readlane_b32 s23, v249, 8
	v_mfma_f32_16x16x32_bf16 v[22:25], v[2:5], v[22:25], 0
	v_readlane_b32 s24, v249, 9
	v_readlane_b32 s25, v249, 10
	v_readlane_b32 s26, v249, 11
	v_mfma_f32_16x16x32_bf16 v[14:17], v[2:5], v[14:17], 0
	v_readlane_b32 s27, v249, 12
	v_readlane_b32 s28, v249, 13
	v_readlane_b32 s29, v249, 14
	s_waitcnt lgkmcnt(1)
	v_mfma_f32_16x16x32_bf16 v[2:5], v[2:5], v[42:45], 0
	v_readlane_b32 s30, v249, 15
	v_readlane_b32 s31, v249, 16
	s_mov_b64 s[14:15], s[22:23]
	s_waitcnt lgkmcnt(0)
	v_mfma_f32_16x16x32_bf16 v[2:5], v[6:9], v[88:91], v[2:5]
	ds_read_b128 v[6:9], v126 offset:30592
	ds_read_b128 v[42:45], v126 offset:30656
	s_waitcnt vmcnt(17)
	s_waitcnt vmcnt(16)
	s_waitcnt lgkmcnt(1)
	v_mfma_f32_16x16x32_bf16 v[2:5], v[10:13], v[6:9], v[2:5]
	v_lshlrev_b32_e32 v6, 16, v110
	v_add_f32_e32 v7, v161, v22
	v_mul_f32_e32 v6, v7, v6
	v_and_b32_e32 v7, 0xffff0000, v110
	v_add_f32_e32 v8, v161, v23
	v_mul_f32_e32 v7, v8, v7
	v_med3_f32 v6, v6, s1, v128
	v_med3_f32 v7, v7, s1, v128
	v_mov_b32_e32 v11, 0
	v_lshlrev_b32_e32 v8, 16, v111
	v_add_f32_e32 v9, v161, v24
	v_cvt_pk_fp8_f32 v11, v6, v7
	v_mul_f32_e32 v8, v9, v8
	v_and_b32_e32 v9, 0xffff0000, v111
	v_add_f32_e32 v10, v161, v25
	v_mul_f32_e32 v6, v10, v9
	v_med3_f32 v7, v8, s1, v128
	v_med3_f32 v6, v6, s1, v128
	v_cvt_pk_fp8_f32 v11, v7, v6 op_sel:[0,0,1]
	v_lshlrev_b32_e32 v8, 16, v118
	v_add_f32_e32 v9, v160, v14
	v_mul_f32_e32 v8, v9, v8
	v_and_b32_e32 v9, 0xffff0000, v118
	v_add_f32_e32 v10, v160, v15
	v_lshlrev_b64 v[6:7], 11, v[116:117]
	v_and_b32_e32 v231, 0x7f, v116
	v_and_b32_e32 v232, 0xffffff80, v116
	s_movk_i32 s88, 0x90
	v_mad_u32_u24 v233, v231, s88, v230
	v_add_u32_e32 v233, 0x12000, v233
	v_mul_f32_e32 v9, v10, v9
	v_lshl_add_u64 v[6:7], v[142:143], 0, v[6:7]
	v_med3_f32 v8, v8, s1, v128
	v_med3_f32 v9, v9, s1, v128
	v_mov_b32_e32 v13, 0
	s_waitcnt vmcnt(15)
; __device__ __forceinline__ float bf_lo(unsigned w) { return __uint_as_float(w << 16); }
; __device__ __forceinline__ unsigned pk4f8(float a, float b, float c, float d) { int p = __builtin_amdgcn_cvt_pk_fp8_f32(sat8(a), sat8(b), 0, false); p = __builtin_amdgcn_cvt_pk_fp8_f32(sat8(c), sat8(d), p, true); return (unsigned)p; }
; __device__ __forceinline__ float bf_hi(unsigned w) { return __uint_as_float(w & 0xffff0000u); }
; __device__ __forceinline__ void gmlp_compute(GmlpRegs& R, const Args& a, const Ctx& C, int c, int hd) {
;     ...
;     for (int nt = 0; nt < 8; ++nt) { const size_t row = T0 + 16 * nt + fr; const float bs = R.bsv[nt];
;         const float o0 = bf_lo(R.uq[nt].x) * (acc[nt][0] + bs), o1 = bf_hi(R.uq[nt].x) * (acc[nt][1] + bs);
;         const float o2 = bf_lo(R.uq[nt].y) * (acc[nt][2] + bs), o3 = bf_hi(R.uq[nt].y) * (acc[nt][3] + bs);
;         *(unsigned*)((unsigned char*)Y + row * DM + chs) = pk4f8(o0, o1, o2, o3); }
	s_waitcnt vmcnt(14)
	s_waitcnt vmcnt(13)
	s_waitcnt vmcnt(12)
	s_waitcnt vmcnt(11)
	s_waitcnt vmcnt(10)
	ds_write_b32 v233, v11
	v_lshlrev_b32_e32 v10, 16, v119
	v_add_f32_e32 v11, v160, v16
	v_cvt_pk_fp8_f32 v13, v8, v9
	v_mul_f32_e32 v10, v11, v10
	v_and_b32_e32 v11, 0xffff0000, v119
	v_add_f32_e32 v12, v160, v17
	v_mul_f32_e32 v8, v12, v11
	v_med3_f32 v9, v10, s1, v128
	v_med3_f32 v8, v8, s1, v128
	v_cvt_pk_fp8_f32 v13, v9, v8 op_sel:[0,0,1]
	v_add_co_u32_e32 v8, vcc, s2, v6
	v_add_f32_e32 v10, v159, v27
	s_nop 0
	v_addc_co_u32_e32 v9, vcc, 0, v7, vcc
	ds_write_b32 v233, v13 offset:2304
	v_lshlrev_b32_e32 v8, 16, v114
	v_add_f32_e32 v9, v159, v26
	v_mul_f32_e32 v8, v9, v8
	v_and_b32_e32 v9, 0xffff0000, v114
	v_mul_f32_e32 v9, v10, v9
	v_med3_f32 v8, v8, s1, v128
	v_med3_f32 v9, v9, s1, v128
	v_mov_b32_e32 v13, 0
	v_lshlrev_b32_e32 v10, 16, v115
	v_add_f32_e32 v11, v159, v28
	v_cvt_pk_fp8_f32 v13, v8, v9
	v_mul_f32_e32 v10, v11, v10
	v_and_b32_e32 v11, 0xffff0000, v115
	v_add_f32_e32 v12, v159, v29
	v_mul_f32_e32 v8, v12, v11
	v_med3_f32 v9, v10, s1, v128
	v_med3_f32 v8, v8, s1, v128
	v_cvt_pk_fp8_f32 v13, v9, v8 op_sel:[0,0,1]
	v_add_co_u32_e32 v8, vcc, s33, v6
	v_add_f32_e32 v10, v156, v19
	s_nop 0
	v_addc_co_u32_e32 v9, vcc, 0, v7, vcc
	ds_write_b32 v233, v13 offset:4608
	v_lshlrev_b32_e32 v8, 16, v108
	v_add_f32_e32 v9, v156, v18
	v_mul_f32_e32 v8, v9, v8
	v_and_b32_e32 v9, 0xffff0000, v108
	v_mul_f32_e32 v9, v10, v9
	v_med3_f32 v8, v8, s1, v128
	v_med3_f32 v9, v9, s1, v128
	v_mov_b32_e32 v13, 0
	v_lshlrev_b32_e32 v10, 16, v109
	v_add_f32_e32 v11, v156, v20
	v_cvt_pk_fp8_f32 v13, v8, v9
	v_mul_f32_e32 v10, v11, v10
	v_and_b32_e32 v11, 0xffff0000, v109
	v_add_f32_e32 v12, v156, v21
	v_mul_f32_e32 v8, v12, v11
	v_med3_f32 v9, v10, s1, v128
	v_med3_f32 v8, v8, s1, v128
	v_cvt_pk_fp8_f32 v13, v9, v8 op_sel:[0,0,1]
	v_add_co_u32_e32 v8, vcc, s74, v6
	v_add_f32_e32 v10, v154, v39
	s_nop 0
	v_addc_co_u32_e32 v9, vcc, 0, v7, vcc
	ds_write_b32 v233, v13 offset:6912
	v_lshlrev_b32_e32 v8, 16, v106
	v_add_f32_e32 v9, v154, v38
	v_mul_f32_e32 v8, v9, v8
	v_and_b32_e32 v9, 0xffff0000, v106
	v_mul_f32_e32 v9, v10, v9
	v_med3_f32 v8, v8, s1, v128
	v_med3_f32 v9, v9, s1, v128
	v_mov_b32_e32 v13, 0
	v_lshlrev_b32_e32 v10, 16, v107
	v_add_f32_e32 v11, v154, v40
	v_cvt_pk_fp8_f32 v13, v8, v9
	v_mul_f32_e32 v10, v11, v10
	v_and_b32_e32 v11, 0xffff0000, v107
	v_add_f32_e32 v12, v154, v41
	v_mul_f32_e32 v8, v12, v11
	v_med3_f32 v9, v10, s1, v128
	v_med3_f32 v8, v8, s1, v128
	v_cvt_pk_fp8_f32 v13, v9, v8 op_sel:[0,0,1]
	v_add_co_u32_e32 v8, vcc, s75, v6
	v_add_f32_e32 v10, v152, v35
	s_nop 0
	v_addc_co_u32_e32 v9, vcc, 0, v7, vcc
	ds_write_b32 v233, v13 offset:9216
	v_lshlrev_b32_e32 v8, 16, v104
	v_add_f32_e32 v9, v152, v34
	v_mul_f32_e32 v8, v9, v8
	v_and_b32_e32 v9, 0xffff0000, v104
	v_mul_f32_e32 v9, v10, v9
	v_med3_f32 v8, v8, s1, v128
	v_med3_f32 v9, v9, s1, v128
	v_mov_b32_e32 v13, 0
	v_lshlrev_b32_e32 v10, 16, v105
	v_add_f32_e32 v11, v152, v36
	v_cvt_pk_fp8_f32 v13, v8, v9
	v_mul_f32_e32 v10, v11, v10
	v_and_b32_e32 v11, 0xffff0000, v105
	v_add_f32_e32 v12, v152, v37
	v_mul_f32_e32 v8, v12, v11
	v_med3_f32 v9, v10, s1, v128
	v_med3_f32 v8, v8, s1, v128
	v_cvt_pk_fp8_f32 v13, v9, v8 op_sel:[0,0,1]
	v_add_co_u32_e32 v8, vcc, s76, v6
	v_add_f32_e32 v10, v151, v31
	s_nop 0
	v_addc_co_u32_e32 v9, vcc, 0, v7, vcc
	ds_write_b32 v233, v13 offset:11520
	v_lshlrev_b32_e32 v8, 16, v102
	v_add_f32_e32 v9, v151, v30
	v_mul_f32_e32 v8, v9, v8
	v_and_b32_e32 v9, 0xffff0000, v102
	v_mul_f32_e32 v9, v10, v9
	v_med3_f32 v8, v8, s1, v128
	v_med3_f32 v9, v9, s1, v128
	v_mov_b32_e32 v13, 0
	v_lshlrev_b32_e32 v10, 16, v103
	v_add_f32_e32 v11, v151, v32
	v_cvt_pk_fp8_f32 v13, v8, v9
	v_mul_f32_e32 v10, v11, v10
	v_and_b32_e32 v11, 0xffff0000, v103
	v_add_f32_e32 v12, v151, v33
	v_mul_f32_e32 v8, v12, v11
	v_med3_f32 v9, v10, s1, v128
	v_med3_f32 v8, v8, s1, v128
	s_waitcnt lgkmcnt(0)
	v_mfma_f32_16x16x32_bf16 v[2:5], v[46:49], v[42:45], v[2:5]
	v_cvt_pk_fp8_f32 v13, v9, v8 op_sel:[0,0,1]
	v_add_co_u32_e32 v8, vcc, s77, v6
	v_mov_b32_e32 v111, 0
	s_nop 0
	v_addc_co_u32_e32 v9, vcc, 0, v7, vcc
	ds_write_b32 v233, v13 offset:13824
	v_lshlrev_b32_e32 v8, 16, v96
	s_nop 0
	v_add_f32_e32 v2, v150, v2
	v_mul_f32_e32 v2, v2, v8
	v_and_b32_e32 v8, 0xffff0000, v96
	v_add_f32_e32 v3, v150, v3
	v_mul_f32_e32 v3, v3, v8
	v_lshlrev_b32_e32 v8, 16, v97
	v_add_f32_e32 v4, v150, v4
	v_mul_f32_e32 v4, v4, v8
	v_and_b32_e32 v8, 0xffff0000, v97
	v_add_f32_e32 v5, v150, v5
	v_med3_f32 v2, v2, s1, v128
	v_med3_f32 v3, v3, s1, v128
	v_mov_b32_e32 v9, 0
	v_cvt_pk_fp8_f32 v9, v2, v3
	v_mul_f32_e32 v2, v5, v8
	v_med3_f32 v3, v4, s1, v128
	v_med3_f32 v2, v2, s1, v128
	s_mul_i32 s1, s0, 0x2100
	s_add_u32 s4, s1, s4
	s_addc_u32 s5, 0, s5
	s_lshl_b64 s[4:5], s[4:5], 5
	s_lshl_b32 s1, s0, 9
	s_lshl_b32 s2, s0, 12
	s_add_u32 s6, s94, s1
	v_cvt_pk_fp8_f32 v9, v3, v2 op_sel:[0,0,1]
	v_add_co_u32_e32 v2, vcc, s78, v6
	v_lshlrev_b32_e32 v110, 2, v153
	s_addc_u32 s7, s95, 0
	v_addc_co_u32_e32 v3, vcc, 0, v7, vcc
	v_lshl_add_u64 v[18:19], s[6:7], 0, v[110:111]
	s_mov_b32 s1, 0x2300000
	v_lshl_add_u64 v[20:21], v[18:19], 0, s[8:9]
	v_add_co_u32_e32 v18, vcc, s1, v18
	ds_write_b32 v233, v9 offset:16128
	s_waitcnt lgkmcnt(0)
	s_barrier
; #define LAS __attribute__((address_space(3)))
; #define PIN(x) asm volatile("" : "+v"(x))
; __device__ __forceinline__ unsigned pk2(float lo, float hi) { return pg8::cvt_pk_bf16(lo, hi); }
; __device__ __forceinline__ bf16x8 pack8(f32x4 lo, f32x4 hi) { v4u w; w.x = pk2(lo[0], lo[1]); w.y = pk2(lo[2], lo[3]); w.z = pk2(hi[0], hi[1]); w.w = pk2(hi[2], hi[3]); return __builtin_bit_cast(bf16x8, w); }
; __device__ __forceinline__ void s5_load_consts(S5C& K, const Args& a, int g, int lane) {
;     const int fr = lane & 15, q = lane >> 4;
;     const float* ABAR = (const float*)(a.ws + WS_S5C + S5C_ABAR) + (size_t)g * 128;
;     const bf16* BBAR = (const bf16*)(a.ws + WS_S5C + S5C_BBAR) + (size_t)g * 2048;
; #pragma unroll
;     for (int j = 0; j < 4; ++j) { const f32x4 x0 = *(const f32x4*)(ABAR + 2 * (16 * j + 4 * q)), x1 = *(const f32x4*)(ABAR + 2 * (16 * j + 4 * q) + 4);
;         K.ar[j] = (f32x4){x0[0], x0[2], x1[0], x1[2]}; K.ai[j] = (f32x4){x0[1], x0[3], x1[1], x1[3]}; }
; #pragma unroll
;     for (int mt = 0; mt < 8; ++mt) K.Bf[mt] = *(const v2u*)(BBAR + (mt * 16 + fr) * 16 + 4 * q);
;     const float* cre = a.in[I_CRE] + ((size_t)g * 16 + fr) * 64; const float* cim = a.in[I_CIM] + ((size_t)g * 16 + fr) * 64;
; #pragma unroll
;     for (int j = 0; j < 4; ++j) { const f32x4 r4 = *(const f32x4*)(cre + 16 * j + 4 * q), i4 = *(const f32x4*)(cim + 16 * j + 4 * q); K.Cf[j] = pack8(r4, -i4); }
;     const float* wg = a.in[I_WGLU] + (size_t)g * 512;
;     { f32x4 v, gt;
; #pragma unroll
;       for (int e = 0; e < 4; ++e) { v[e] = wg[(4 * q + e) * 32 + fr]; gt[e] = wg[(4 * q + e) * 32 + 16 + fr]; }
;       K.Wv = (v2u){pk2(v[0], v[1]), pk2(v[2], v[3])}; K.Wg = (v2u){pk2(gt[0], gt[1]), pk2(gt[2], gt[3])}; }
;     K.dsk = *(const f32x4*)(a.in[I_DSKIP] + g * 16 + 4 * q);
;     K.bv = *(const f32x4*)(a.in[I_BGLU] + g * 32 + 4 * q); K.bg = *(const f32x4*)(a.in[I_BGLU] + g * 32 + 16 + 4 * q);
; __device__ __forceinline__ void s5_prompt_task(const Args& a, const Ctx& C, int b, int g, v4u (&xv)[8]) {
;     ...
;     __syncthreads();
; #pragma unroll
;     for (int i = 0; i < 8; ++i) PIN(xv[i]);
; #pragma unroll
;     for (int i = 0; i < 8; ++i) { const int idx = C.tid + 512 * i, tok = idx >> 1; *(LAS v4u*)(XS + tok * 32 + (tok >> 4) * 16 + (idx & 1) * 16) = xv[i]; }
;     S5C K; s5_load_consts(K, a, g, lane);
;     __syncthreads();
	v_lshrrev_b32_e32 v234, 3, v0
	v_and_b32_e32 v236, 7, v0
	v_lshlrev_b32_e32 v236, 4, v236
	s_movk_i32 s88, 0x90
	v_mad_u32_u24 v221, v234, s88, v236
	v_add_u32_e32 v221, 0x12000, v221
	ds_read_b128 v[238:241], v221
	ds_read_b128 v[242:245], v221 offset:9216
	v_add_u32_e32 v234, v232, v234
	v_mov_b32_e32 v235, 0
	v_mov_b32_e32 v237, 0
	v_lshlrev_b64 v[246:247], 11, v[234:235]
	v_lshl_add_u64 v[246:247], v[228:229], 0, v[246:247]
	v_lshl_add_u64 v[246:247], v[246:247], 0, v[236:237]
	v_mov_b32_e32 v236, 0x20000
	v_lshl_add_u64 v[212:213], v[246:247], 0, v[236:237]
	s_waitcnt lgkmcnt(0)
	global_store_dwordx4 v[246:247], v[238:241], off
	global_store_dwordx4 v[212:213], v[242:245], off
	s_nop 0
	v_addc_co_u32_e32 v19, vcc, 0, v19, vcc
	s_barrier
	s_waitcnt vmcnt(9)
	s_waitcnt vmcnt(8)
	s_waitcnt vmcnt(7)
	s_waitcnt vmcnt(6)
	s_waitcnt vmcnt(5)
	s_waitcnt vmcnt(4)
	s_waitcnt vmcnt(3)
	s_waitcnt vmcnt(2)
	global_load_dwordx4 v[2:5], v[20:21], off offset:16
	global_load_dwordx4 v[6:9], v[20:21], off offset:144
	global_load_dwordx4 v[10:13], v[20:21], off offset:272
	global_load_dwordx4 v[14:17], v[20:21], off offset:400
	global_load_dwordx4 v[30:33], v[18:19], off
	v_and_b32_e32 v18, 0x1fe0, v94
	v_lshrrev_b32_e32 v19, 1, v0
	v_add_u32_e32 v18, 0, v18
	v_and_b32_e32 v19, 0xf0, v19
	v_and_b32_e32 v24, 16, v94
	v_add3_u32 v18, v18, v19, v24
	ds_write_b128 v18, v[74:77]
	v_and_b32_e32 v18, 0x3fe0, v87
	v_lshrrev_b32_e32 v19, 1, v146
	v_add_u32_e32 v18, 0, v18
	v_and_b32_e32 v19, 0x1f0, v19
	v_add3_u32 v18, v18, v19, v24
	ds_write_b128 v18, v[78:81]
	v_and_b32_e32 v18, 0x7fe0, v148
	v_lshrrev_b32_e32 v19, 1, v147
	v_add_u32_e32 v18, 0, v18
	v_and_b32_e32 v19, 0x3f0, v19
	v_add3_u32 v18, v18, v19, v24
	ds_write_b128 v18, v[70:73]
	v_and_b32_e32 v18, 0x7fe0, v86
	v_lshrrev_b32_e32 v19, 1, v95
	v_add_u32_e32 v18, 0, v18
	v_and_b32_e32 v19, 0x3f0, v19
	v_add3_u32 v18, v18, v19, v24
	ds_write_b128 v18, v[66:69]
	v_and_b32_e32 v18, 0xbfe0, v85
	v_lshrrev_b32_e32 v19, 1, v120
	v_add_u32_e32 v18, 0, v18
	v_and_b32_e32 v19, 0x5f0, v19
	v_add3_u32 v18, v18, v19, v24
	ds_write_b128 v18, v[58:61]
	v_and_b32_e32 v18, 0xffe0, v84
	v_lshrrev_b32_e32 v19, 1, v157
	v_add_u32_e32 v18, 0, v18
	v_and_b32_e32 v19, 0x7f0, v19
	v_add3_u32 v18, v18, v19, v24
	ds_write_b128 v18, v[62:65]
	v_and_b32_e32 v18, 0xffe0, v83
	v_lshrrev_b32_e32 v19, 1, v158
	s_add_u32 s8, s94, s2
	v_add_u32_e32 v18, 0, v18
	v_and_b32_e32 v19, 0x7f0, v19
	s_addc_u32 s9, s95, 0
	v_lshlrev_b32_e32 v110, 1, v112
	v_add3_u32 v25, v18, v19, v24
	v_lshl_add_u64 v[18:19], s[8:9], 0, v[110:111]
	v_lshlrev_b32_e32 v22, 5, v149
	v_mov_b32_e32 v23, v111
	v_lshl_add_u64 v[18:19], v[18:19], 0, v[22:23]
	s_mov_b32 s1, 0x2320000
	v_add_co_u32_e32 v22, vcc, s1, v18
	s_mov_b64 s[8:9], 0x2320000
	s_nop 0
	v_addc_co_u32_e32 v23, vcc, 0, v19, vcc
	global_load_dwordx2 v[114:115], v[22:23], off
	v_lshl_add_u64 v[18:19], v[18:19], 0, s[8:9]
	global_load_dwordx2 v[116:117], v[18:19], off offset:512
	global_load_dwordx4 v[70:73], v[20:21], off offset:128
	v_and_b32_e32 v22, 0xffe0, v82
	v_lshrrev_b32_e32 v23, 1, v155
	global_load_dwordx4 v[74:77], v[20:21], off offset:256
	global_load_dwordx4 v[66:69], v[20:21], off offset:384
	v_add_u32_e32 v22, 0, v22
	v_and_b32_e32 v23, 0x7f0, v23
	v_add3_u32 v22, v22, v23, v24
	ds_write_b128 v25, v[50:53]
	ds_write_b128 v22, v[54:57]
	global_load_dwordx2 v[126:127], v[18:19], off offset:1024
	global_load_dwordx2 v[128:129], v[18:19], off offset:1536
	global_load_dwordx2 v[130:131], v[18:19], off offset:2048
	global_load_dwordx2 v[132:133], v[18:19], off offset:2560
	global_load_dwordx2 v[134:135], v[18:19], off offset:3072
	global_load_dwordx2 v[136:137], v[18:19], off offset:3584
	v_lshl_or_b32 v18, v149, 8, s2
	v_mov_b32_e32 v19, v111
	s_mov_b64 s[16:17], s[24:25]
	v_lshl_add_u64 v[20:21], s[14:15], 0, v[18:19]
	v_lshl_add_u64 v[18:19], s[16:17], 0, v[18:19]
	v_lshlrev_b32_e32 v78, 2, v112
	v_mov_b32_e32 v79, v111
	s_mov_b64 s[20:21], s[28:29]
	v_lshl_add_u64 v[20:21], v[20:21], 0, v[78:79]
	v_lshl_add_u64 v[18:19], v[18:19], 0, v[78:79]
	s_lshl_b32 s1, s0, 11
	s_add_u32 s8, s20, s1
	v_lshlrev_b32_e32 v18, 2, v149
	s_mov_b64 s[18:19], s[26:27]
	s_addc_u32 s9, s21, 0
	v_lshl_or_b32 v18, v145, 9, v18
	s_lshl_b32 s1, s0, 4
	s_lshl_b32 s2, s0, 6
	s_add_u32 s8, s18, s2
	s_mov_b64 s[22:23], s[30:31]
	s_addc_u32 s9, s19, 0
	s_lshl_b32 s2, s0, 7
	s_add_u32 s10, s22, s2
	s_movk_i32 s2, 0x210
	v_mul_lo_u32 v102, v144, s2
	v_add3_u32 v163, 0, v102, v153
	s_addc_u32 s11, s23, 0
	v_readlane_b32 s36, v249, 0
	s_and_b32 s36, s36, 63
	s_lshl_b32 s36, s36, 9
	s_add_u32 s36, s36, 0x2308000
	s_add_u32 s36, s94, s36
	s_addc_u32 s37, s95, 0
	s_add_u32 s38, s36, 0x8000
	s_addc_u32 s39, s37, 0
	v_lshlrev_b32_e32 v238, 3, v162
	s_nop 1
	global_load_dwordx2 v[234:235], v238, s[36:37]
	global_load_dwordx2 v[236:237], v238, s[38:39]
	s_waitcnt lgkmcnt(0)
	s_barrier
; #define LAS __attribute__((address_space(3)))
; #define S5_UPDATE(K, hre, him, xq) do { const v2u xb_ = (xq); \
;     _Pragma("unroll") for (int j = 0; j < 4; ++j) { const f32x4 cre_ = K.ar[j] * hre[j] - K.ai[j] * him[j], cim_ = K.ar[j] * him[j] + K.ai[j] * hre[j]; \
;         hre[j] = MFMA16K16(K.Bf[2 * j], xb_, cre_); him[j] = MFMA16K16(K.Bf[2 * j + 1], xb_, cim_); } } while (0)
; __device__ __forceinline__ void s5_prompt_task(const Args& a, const Ctx& C, int b, int g, v4u (&xv)[8]) {
;     ...
;     const int chunk = 16 * w + n;
;     f32x4 hre[4], him[4];
; #pragma unroll
;     for (int j = 0; j < 4; ++j) { hre[j] = (f32x4){0.f, 0.f, 0.f, 0.f}; him[j] = (f32x4){0.f, 0.f, 0.f, 0.f}; }
;     const LAS unsigned char* xsl = XS + chunk * 528 + q * 8;
;     for (int t = 0; t < 16; ++t) { const v2u xq = *(const LAS v2u*)(xsl + t * 32); S5_UPDATE(K, hre, him, xq); }
	ds_read2_b64 v[104:107], v163 offset1:4
	s_waitcnt vmcnt(13)
	v_mov_b32_e32 v78, v30
	v_mov_b32_e32 v79, v32
	v_mov_b32_e32 v80, v2
	v_mov_b32_e32 v81, v4
	v_pk_mul_f32 v[86:87], v[78:79], 0 op_sel_hi:[1,0]
	v_pk_mul_f32 v[90:91], v[80:81], 0 op_sel_hi:[1,0]
	v_xor_b32_e32 v83, 0x80000000, v33
	v_xor_b32_e32 v82, 0x80000000, v31
	v_xor_b32_e32 v85, 0x80000000, v5
	v_xor_b32_e32 v84, 0x80000000, v3
	v_mov_b32_e32 v118, v3
	v_pk_fma_f32 v[82:83], v[82:83], 0, v[86:87] op_sel_hi:[1,0,1]
	v_pk_fma_f32 v[84:85], v[84:85], 0, v[90:91] op_sel_hi:[1,0,1]
	v_mov_b32_e32 v88, v31
	v_mov_b32_e32 v89, v33
	v_mov_b32_e32 v119, v5
	s_waitcnt vmcnt(12) lgkmcnt(0)
	v_mfma_f32_16x16x16_bf16 v[138:141], v[114:115], v[104:105], v[82:85]
	s_nop 2
	v_fma_f32 v82, v88, 0, v86
	v_fma_f32 v83, v89, 0, v87
	v_pk_fma_f32 v[84:85], v[118:119], 0, v[90:91] op_sel_hi:[1,0,1]
	v_mov_b32_e32 v86, v6
	v_mov_b32_e32 v87, v8
	s_waitcnt vmcnt(11)
	v_mfma_f32_16x16x16_bf16 v[146:149], v[116:117], v[104:105], v[82:85]
	v_mul_f32_e64 v94, v86, 0
	v_mul_f32_e64 v95, v87, 0
	v_xor_b32_e32 v91, 0x80000000, v9
	v_xor_b32_e32 v90, 0x80000000, v7
	s_waitcnt vmcnt(10)
	v_mov_b32_e32 v82, v70
	v_mov_b32_e32 v83, v72
	v_mov_b32_e32 v120, v7
	v_pk_mul_f32 v[84:85], v[82:83], 0 op_sel_hi:[1,0]
	v_pk_fma_f32 v[92:93], v[90:91], 0, v[94:95] op_sel_hi:[1,0,1]
	v_xor_b32_e32 v91, 0x80000000, v73
	v_xor_b32_e32 v90, 0x80000000, v71
	v_mov_b32_e32 v121, v9
	v_pk_fma_f32 v[90:91], v[90:91], 0, v[84:85] op_sel_hi:[1,0,1]
	v_pk_fma_f32 v[98:99], v[120:121], 0, v[94:95] op_sel_hi:[1,0,1]
	v_mov_b32_e32 v94, v71
	v_mov_b32_e32 v95, v73
	s_waitcnt vmcnt(7)
	v_mfma_f32_16x16x16_bf16 v[150:153], v[126:127], v[104:105], v[90:93]
	v_fma_f32 v96, v94, 0, v84
	v_fma_f32 v97, v95, 0, v85
	v_mov_b32_e32 v84, v74
	v_mov_b32_e32 v85, v76
	v_mov_b32_e32 v92, v10
	v_mov_b32_e32 v93, v12
	s_waitcnt vmcnt(6)
	v_mfma_f32_16x16x16_bf16 v[154:157], v[128:129], v[104:105], v[96:99]
	v_mul_f32_e64 v100, v92, 0
	v_mul_f32_e64 v101, v93, 0
	v_pk_mul_f32 v[90:91], v[84:85], 0 op_sel_hi:[1,0]
	v_mov_b32_e32 v122, v11
	v_xor_b32_e32 v97, 0x80000000, v13
	v_xor_b32_e32 v96, 0x80000000, v11
	v_pk_fma_f32 v[98:99], v[96:97], 0, v[100:101] op_sel_hi:[1,0,1]
	v_xor_b32_e32 v97, 0x80000000, v77
	v_xor_b32_e32 v96, 0x80000000, v75
	v_pk_fma_f32 v[96:97], v[96:97], 0, v[90:91] op_sel_hi:[1,0,1]
	v_mov_b32_e32 v123, v13
	v_pk_fma_f32 v[166:167], v[122:123], 0, v[100:101] op_sel_hi:[1,0,1]
	s_waitcnt vmcnt(5)
	v_mfma_f32_16x16x16_bf16 v[168:171], v[130:131], v[104:105], v[96:99]
	v_xor_b32_e32 v143, 0x80000000, v17
	v_xor_b32_e32 v142, 0x80000000, v15
	v_mov_b32_e32 v124, v15
	v_mov_b32_e32 v98, v75
	v_mov_b32_e32 v99, v77
	v_mov_b32_e32 v96, v14
	v_mov_b32_e32 v97, v16
	v_pk_fma_f32 v[164:165], v[98:99], 0, v[90:91] op_sel_hi:[1,0,1]
	v_mov_b32_e32 v90, v66
	v_mov_b32_e32 v91, v68
	v_pk_mul_f32 v[100:101], v[96:97], 0 op_sel_hi:[1,0]
	v_pk_mul_f32 v[108:109], v[90:91], 0 op_sel_hi:[1,0]
	v_pk_fma_f32 v[174:175], v[142:143], 0, v[100:101] op_sel_hi:[1,0,1]
	v_xor_b32_e32 v143, 0x80000000, v69
	v_xor_b32_e32 v142, 0x80000000, v67
	v_mov_b32_e32 v125, v17
	v_pk_fma_f32 v[172:173], v[142:143], 0, v[108:109] op_sel_hi:[1,0,1]
	v_pk_fma_f32 v[176:177], v[124:125], 0, v[100:101] op_sel_hi:[1,0,1]
	v_mov_b32_e32 v100, v67
	v_mov_b32_e32 v101, v69
	s_waitcnt vmcnt(3)
	v_mfma_f32_16x16x16_bf16 v[178:181], v[134:135], v[104:105], v[172:175]
	s_add_i32 s8, 0, 0x10800
	v_add_u32_e32 v3, s8, v102
	v_lshlrev_b32_e32 v7, 5, v145
	v_pk_fma_f32 v[174:175], v[100:101], 0, v[108:109] op_sel_hi:[1,0,1]
	v_mfma_f32_16x16x16_bf16 v[164:167], v[132:133], v[104:105], v[164:167]
	v_mul_f32_e64 v108, v88, v146
	v_mul_f32_e64 v109, v89, v147
	v_add_u32_e32 v3, v3, v7
	v_pk_fma_f32 v[182:183], v[78:79], v[138:139], v[108:109] neg_lo:[0,0,1] neg_hi:[0,0,1]
	s_waitcnt vmcnt(2)
	v_mfma_f32_16x16x16_bf16 v[172:175], v[136:137], v[104:105], v[174:177]
	v_mul_f32_e64 v104, v118, v148
	v_mul_f32_e64 v105, v119, v149
	v_pk_mul_f32 v[108:109], v[78:79], v[146:147]
	v_pk_fma_f32 v[184:185], v[80:81], v[140:141], v[104:105] neg_lo:[0,0,1] neg_hi:[0,0,1]
	v_pk_mul_f32 v[104:105], v[80:81], v[148:149]
	v_pk_fma_f32 v[138:139], v[88:89], v[138:139], v[108:109]
	v_pk_fma_f32 v[140:141], v[118:119], v[140:141], v[104:105]
	v_pk_mul_f32 v[104:105], v[120:121], v[156:157]
	v_pk_mul_f32 v[108:109], v[94:95], v[154:155]
	v_pk_fma_f32 v[148:149], v[86:87], v[152:153], v[104:105] neg_lo:[0,0,1] neg_hi:[0,0,1]
	v_pk_fma_f32 v[146:147], v[82:83], v[150:151], v[108:109] neg_lo:[0,0,1] neg_hi:[0,0,1]
	v_pk_mul_f32 v[104:105], v[86:87], v[156:157]
	v_pk_mul_f32 v[108:109], v[82:83], v[154:155]
	v_pk_fma_f32 v[152:153], v[120:121], v[152:153], v[104:105]
	v_pk_fma_f32 v[150:151], v[94:95], v[150:151], v[108:109]
	v_pk_mul_f32 v[104:105], v[122:123], v[166:167]
	v_pk_mul_f32 v[108:109], v[98:99], v[164:165]
	v_pk_fma_f32 v[156:157], v[92:93], v[170:171], v[104:105] neg_lo:[0,0,1] neg_hi:[0,0,1]
	v_pk_fma_f32 v[154:155], v[84:85], v[168:169], v[108:109] neg_lo:[0,0,1] neg_hi:[0,0,1]
	v_pk_mul_f32 v[104:105], v[92:93], v[166:167]
	v_pk_mul_f32 v[108:109], v[84:85], v[164:165]
	v_pk_fma_f32 v[166:167], v[122:123], v[170:171], v[104:105]
	v_pk_fma_f32 v[164:165], v[98:99], v[168:169], v[108:109]
	v_pk_mul_f32 v[104:105], v[124:125], v[174:175]
	v_pk_mul_f32 v[108:109], v[100:101], v[172:173]
	v_pk_fma_f32 v[170:171], v[96:97], v[180:181], v[104:105] neg_lo:[0,0,1] neg_hi:[0,0,1]
	v_pk_fma_f32 v[168:169], v[90:91], v[178:179], v[108:109] neg_lo:[0,0,1] neg_hi:[0,0,1]
	v_pk_mul_f32 v[104:105], v[96:97], v[174:175]
	v_pk_mul_f32 v[108:109], v[90:91], v[172:173]
	v_mfma_f32_16x16x16_bf16 v[138:141], v[116:117], v[106:107], v[138:141]
	v_fma_f32 v174, v124, v180, v104
	v_fma_f32 v175, v125, v181, v105
	v_pk_fma_f32 v[172:173], v[100:101], v[178:179], v[108:109]
	s_add_u32 s4, s94, s4
	v_mfma_f32_16x16x16_bf16 v[182:185], v[114:115], v[106:107], v[182:185]
	s_addc_u32 s5, s95, s5
	s_nop 1
	v_pk_mul_f32 v[108:109], v[118:119], v[140:141]
	v_pk_mul_f32 v[142:143], v[88:89], v[138:139]
	v_mfma_f32_16x16x16_bf16 v[146:149], v[126:127], v[106:107], v[146:149]
	v_mul_f32_e64 v138, v78, v138
	v_mul_f32_e64 v139, v79, v139
	v_pk_fma_f32 v[178:179], v[80:81], v[184:185], v[108:109] neg_lo:[0,0,1] neg_hi:[0,0,1]
	v_pk_fma_f32 v[176:177], v[78:79], v[182:183], v[142:143] neg_lo:[0,0,1] neg_hi:[0,0,1]
	v_mfma_f32_16x16x16_bf16 v[150:153], v[128:129], v[106:107], v[150:153]
	v_mul_f32_e64 v108, v80, v140
	v_mul_f32_e64 v109, v81, v141
	v_lshlrev_b32_e32 v7, 4, v144
	s_mov_b32 s2, 0x2308000
	v_mfma_f32_16x16x16_bf16 v[154:157], v[130:131], v[106:107], v[154:157]
	v_mov_b32_e32 v160, v111
	v_mfma_f32_16x16x16_bf16 v[164:167], v[132:133], v[106:107], v[164:167]
	v_mfma_f32_16x16x16_bf16 v[168:171], v[134:135], v[106:107], v[168:171]
	v_mfma_f32_16x16x16_bf16 v[104:107], v[136:137], v[106:107], v[172:175]
	s_nop 2
	ds_read2_b64 v[172:175], v163 offset0:8 offset1:12
	s_waitcnt lgkmcnt(0)
; #define LAS __attribute__((address_space(3)))
; #define S5_UPDATE(K, hre, him, xq) do { const v2u xb_ = (xq); \
;     _Pragma("unroll") for (int j = 0; j < 4; ++j) { const f32x4 cre_ = K.ar[j] * hre[j] - K.ai[j] * him[j], cim_ = K.ar[j] * him[j] + K.ai[j] * hre[j]; \
;         hre[j] = MFMA16K16(K.Bf[2 * j], xb_, cre_); him[j] = MFMA16K16(K.Bf[2 * j + 1], xb_, cim_); } } while (0)
; __device__ __forceinline__ void s5_prompt_task(const Args& a, const Ctx& C, int b, int g, v4u (&xv)[8]) {
;     ...
;     for (int t = 0; t < 16; ++t) { const v2u xq = *(const LAS v2u*)(xsl + t * 32); S5_UPDATE(K, hre, him, xq); }
	v_mfma_f32_16x16x16_bf16 v[140:143], v[114:115], v[172:173], v[176:179]
	s_nop 2
	v_fma_f32 v178, v118, v184, v108
	v_fma_f32 v179, v119, v185, v109
	v_pk_fma_f32 v[176:177], v[88:89], v[182:183], v[138:139]
	v_pk_mul_f32 v[108:109], v[120:121], v[152:153]
	v_pk_mul_f32 v[138:139], v[94:95], v[150:151]
	v_pk_fma_f32 v[182:183], v[86:87], v[148:149], v[108:109] neg_lo:[0,0,1] neg_hi:[0,0,1]
	v_pk_fma_f32 v[180:181], v[82:83], v[146:147], v[138:139] neg_lo:[0,0,1] neg_hi:[0,0,1]
	v_pk_mul_f32 v[108:109], v[86:87], v[152:153]
	v_pk_mul_f32 v[138:139], v[82:83], v[150:151]
	v_mfma_f32_16x16x16_bf16 v[176:179], v[116:117], v[172:173], v[176:179]
	v_fma_f32 v148, v120, v148, v108
	v_fma_f32 v149, v121, v149, v109
	v_pk_fma_f32 v[146:147], v[94:95], v[146:147], v[138:139]
	v_pk_mul_f32 v[108:109], v[122:123], v[166:167]
	v_pk_mul_f32 v[138:139], v[98:99], v[164:165]
	v_pk_fma_f32 v[152:153], v[92:93], v[156:157], v[108:109] neg_lo:[0,0,1] neg_hi:[0,0,1]
	v_pk_fma_f32 v[150:151], v[84:85], v[154:155], v[138:139] neg_lo:[0,0,1] neg_hi:[0,0,1]
	v_pk_mul_f32 v[108:109], v[92:93], v[166:167]
	v_pk_mul_f32 v[138:139], v[84:85], v[164:165]
	v_pk_fma_f32 v[156:157], v[122:123], v[156:157], v[108:109]
	v_pk_fma_f32 v[154:155], v[98:99], v[154:155], v[138:139]
	v_pk_mul_f32 v[108:109], v[124:125], v[106:107]
	v_pk_mul_f32 v[138:139], v[100:101], v[104:105]
	v_mfma_f32_16x16x16_bf16 v[146:149], v[128:129], v[172:173], v[146:149]
	v_fma_f32 v166, v96, v170, -v108
	v_fma_f32 v167, v97, v171, -v109
	v_pk_fma_f32 v[164:165], v[90:91], v[168:169], v[138:139] neg_lo:[0,0,1] neg_hi:[0,0,1]
	v_pk_mul_f32 v[138:139], v[96:97], v[106:107]
	v_pk_mul_f32 v[104:105], v[90:91], v[104:105]
	v_mfma_f32_16x16x16_bf16 v[180:183], v[126:127], v[172:173], v[180:183]
	v_mfma_f32_16x16x16_bf16 v[106:109], v[134:135], v[172:173], v[164:167]
	s_nop 2
	v_fma_f32 v166, v124, v170, v138
	v_fma_f32 v167, v125, v171, v139
	v_pk_fma_f32 v[164:165], v[100:101], v[168:169], v[104:105]
	v_pk_mul_f32 v[104:105], v[118:119], v[178:179]
	v_pk_mul_f32 v[138:139], v[88:89], v[176:177]
	v_mfma_f32_16x16x16_bf16 v[154:157], v[132:133], v[172:173], v[154:157]
	v_fma_f32 v170, v80, v142, -v104
	v_fma_f32 v171, v81, v143, -v105
	v_pk_fma_f32 v[168:169], v[78:79], v[140:141], v[138:139] neg_lo:[0,0,1] neg_hi:[0,0,1]
	v_pk_mul_f32 v[104:105], v[80:81], v[178:179]
	v_pk_mul_f32 v[138:139], v[78:79], v[176:177]
	v_mfma_f32_16x16x16_bf16 v[150:153], v[130:131], v[172:173], v[150:153]
	v_fma_f32 v142, v118, v142, v104
	v_fma_f32 v143, v119, v143, v105
	v_pk_fma_f32 v[140:141], v[88:89], v[140:141], v[138:139]
	v_pk_mul_f32 v[104:105], v[120:121], v[148:149]
	v_mfma_f32_16x16x16_bf16 v[164:167], v[136:137], v[172:173], v[164:167]
	v_fma_f32 v178, v86, v182, -v104
	v_fma_f32 v179, v87, v183, -v105
	v_pk_mul_f32 v[104:105], v[86:87], v[148:149]
	v_mfma_f32_16x16x16_bf16 v[138:141], v[116:117], v[174:175], v[140:143]
	v_fma_f32 v148, v120, v182, v104
	v_fma_f32 v149, v121, v183, v105
	v_pk_mul_f32 v[104:105], v[122:123], v[156:157]
	v_pk_mul_f32 v[142:143], v[94:95], v[146:147]
	v_pk_fma_f32 v[182:183], v[92:93], v[152:153], v[104:105] neg_lo:[0,0,1] neg_hi:[0,0,1]
	v_pk_fma_f32 v[176:177], v[82:83], v[180:181], v[142:143] neg_lo:[0,0,1] neg_hi:[0,0,1]
	v_pk_mul_f32 v[142:143], v[82:83], v[146:147]
	v_pk_mul_f32 v[104:105], v[92:93], v[156:157]
	v_pk_fma_f32 v[146:147], v[94:95], v[180:181], v[142:143]
	v_pk_mul_f32 v[142:143], v[98:99], v[154:155]
	v_mfma_f32_16x16x16_bf16 v[168:171], v[114:115], v[174:175], v[168:171]
	v_fma_f32 v180, v84, v150, -v142
	v_fma_f32 v181, v85, v151, -v143
	v_pk_mul_f32 v[142:143], v[84:85], v[154:155]
	v_pk_fma_f32 v[152:153], v[122:123], v[152:153], v[104:105]
	v_pk_fma_f32 v[150:151], v[98:99], v[150:151], v[142:143]
	v_pk_mul_f32 v[104:105], v[124:125], v[166:167]
	v_pk_mul_f32 v[142:143], v[100:101], v[164:165]
	v_mfma_f32_16x16x16_bf16 v[146:149], v[128:129], v[174:175], v[146:149]
	v_mfma_f32_16x16x16_bf16 v[156:159], v[130:131], v[174:175], v[180:183]
	s_nop 2
	v_fma_f32 v182, v96, v108, -v104
	v_fma_f32 v183, v97, v109, -v105
	v_pk_fma_f32 v[180:181], v[90:91], v[106:107], v[142:143] neg_lo:[0,0,1] neg_hi:[0,0,1]
	v_pk_mul_f32 v[104:105], v[96:97], v[166:167]
	v_pk_mul_f32 v[142:143], v[90:91], v[164:165]
	ds_read2_b64 v[164:167], v163 offset0:16 offset1:20
	v_mfma_f32_16x16x16_bf16 v[176:179], v[126:127], v[174:175], v[176:179]
	v_fma_f32 v108, v124, v108, v104
	v_fma_f32 v109, v125, v109, v105
	v_pk_fma_f32 v[106:107], v[100:101], v[106:107], v[142:143]
	v_pk_mul_f32 v[142:143], v[88:89], v[138:139]
	v_mfma_f32_16x16x16_bf16 v[150:153], v[132:133], v[174:175], v[150:153]
	v_mul_f32_e64 v138, v78, v138
	v_mul_f32_e64 v139, v79, v139
	v_pk_fma_f32 v[172:173], v[78:79], v[168:169], v[142:143] neg_lo:[0,0,1] neg_hi:[0,0,1]
	v_pk_fma_f32 v[168:169], v[88:89], v[168:169], v[138:139]
	v_mfma_f32_16x16x16_bf16 v[104:107], v[136:137], v[174:175], v[106:109]
	v_mul_f32_e64 v138, v94, v146
	v_mul_f32_e64 v139, v95, v147
	s_nop 0
	v_pk_mul_f32 v[108:109], v[118:119], v[140:141]
	v_mfma_f32_16x16x16_bf16 v[180:183], v[134:135], v[174:175], v[180:183]
	v_fma_f32 v174, v80, v170, -v108
	v_fma_f32 v175, v81, v171, -v109
	v_pk_mul_f32 v[108:109], v[80:81], v[140:141]
	s_nop 0
	v_pk_fma_f32 v[170:171], v[118:119], v[170:171], v[108:109]
	v_pk_mul_f32 v[108:109], v[120:121], v[148:149]
	s_waitcnt lgkmcnt(0)
; #define LAS __attribute__((address_space(3)))
; #define S5_UPDATE(K, hre, him, xq) do { const v2u xb_ = (xq); \
;     _Pragma("unroll") for (int j = 0; j < 4; ++j) { const f32x4 cre_ = K.ar[j] * hre[j] - K.ai[j] * him[j], cim_ = K.ar[j] * him[j] + K.ai[j] * hre[j]; \
;         hre[j] = MFMA16K16(K.Bf[2 * j], xb_, cre_); him[j] = MFMA16K16(K.Bf[2 * j + 1], xb_, cim_); } } while (0)
; __device__ __forceinline__ void s5_prompt_task(const Args& a, const Ctx& C, int b, int g, v4u (&xv)[8]) {
;     ...
;     for (int t = 0; t < 16; ++t) { const v2u xq = *(const LAS v2u*)(xsl + t * 32); S5_UPDATE(K, hre, him, xq); }
	v_mfma_f32_16x16x16_bf16 v[140:143], v[114:115], v[164:165], v[172:175]
	s_nop 2
	v_fma_f32 v174, v86, v178, -v108
	v_fma_f32 v175, v87, v179, -v109
	v_pk_fma_f32 v[172:173], v[82:83], v[176:177], v[138:139] neg_lo:[0,0,1] neg_hi:[0,0,1]
	v_pk_mul_f32 v[108:109], v[86:87], v[148:149]
	v_pk_mul_f32 v[138:139], v[82:83], v[146:147]
	v_mfma_f32_16x16x16_bf16 v[168:171], v[116:117], v[164:165], v[168:171]
	v_fma_f32 v148, v120, v178, v108
	v_fma_f32 v149, v121, v179, v109
	v_pk_fma_f32 v[146:147], v[94:95], v[176:177], v[138:139]
	v_pk_mul_f32 v[108:109], v[122:123], v[152:153]
	v_pk_mul_f32 v[138:139], v[98:99], v[150:151]
	v_pk_fma_f32 v[178:179], v[92:93], v[158:159], v[108:109] neg_lo:[0,0,1] neg_hi:[0,0,1]
	v_pk_fma_f32 v[176:177], v[84:85], v[156:157], v[138:139] neg_lo:[0,0,1] neg_hi:[0,0,1]
	v_pk_mul_f32 v[108:109], v[92:93], v[152:153]
	v_pk_mul_f32 v[138:139], v[84:85], v[150:151]
	v_pk_fma_f32 v[158:159], v[122:123], v[158:159], v[108:109]
	v_pk_fma_f32 v[156:157], v[98:99], v[156:157], v[138:139]
	v_pk_mul_f32 v[108:109], v[124:125], v[106:107]
	v_pk_mul_f32 v[138:139], v[100:101], v[104:105]
	v_mfma_f32_16x16x16_bf16 v[146:149], v[128:129], v[164:165], v[146:149]
	v_mul_f32_e64 v104, v90, v104
	v_mul_f32_e64 v105, v91, v105
	v_mfma_f32_16x16x16_bf16 v[152:155], v[130:131], v[164:165], v[176:179]
	s_nop 2
	v_fma_f32 v178, v96, v182, -v108
	v_fma_f32 v179, v97, v183, -v109
	v_pk_fma_f32 v[176:177], v[90:91], v[180:181], v[138:139] neg_lo:[0,0,1] neg_hi:[0,0,1]
	v_pk_mul_f32 v[138:139], v[96:97], v[106:107]
	v_mfma_f32_16x16x16_bf16 v[172:175], v[126:127], v[164:165], v[172:175]
	v_mfma_f32_16x16x16_bf16 v[106:109], v[134:135], v[164:165], v[176:179]
	s_nop 2
	v_fma_f32 v178, v124, v182, v138
	v_fma_f32 v179, v125, v183, v139
	v_pk_fma_f32 v[176:177], v[100:101], v[180:181], v[104:105]
	v_pk_mul_f32 v[104:105], v[118:119], v[170:171]
	v_pk_mul_f32 v[138:139], v[88:89], v[168:169]
	v_mfma_f32_16x16x16_bf16 v[156:159], v[132:133], v[164:165], v[156:159]
	v_fma_f32 v182, v80, v142, -v104
	v_fma_f32 v183, v81, v143, -v105
	v_pk_fma_f32 v[180:181], v[78:79], v[140:141], v[138:139] neg_lo:[0,0,1] neg_hi:[0,0,1]
	v_pk_mul_f32 v[104:105], v[80:81], v[170:171]
	v_pk_mul_f32 v[138:139], v[78:79], v[168:169]
	v_pk_fma_f32 v[142:143], v[118:119], v[142:143], v[104:105]
	v_pk_fma_f32 v[140:141], v[88:89], v[140:141], v[138:139]
	v_mfma_f32_16x16x16_bf16 v[176:179], v[136:137], v[164:165], v[176:179]
	v_mul_f32_e64 v104, v120, v148
	v_mul_f32_e64 v105, v121, v149
	v_pk_fma_f32 v[170:171], v[86:87], v[174:175], v[104:105] neg_lo:[0,0,1] neg_hi:[0,0,1]
	v_mfma_f32_16x16x16_bf16 v[138:141], v[116:117], v[166:167], v[140:143]
	v_mul_f32_e64 v104, v86, v148
	v_mul_f32_e64 v105, v87, v149
	s_nop 0
	v_pk_mul_f32 v[142:143], v[94:95], v[146:147]
	v_mfma_f32_16x16x16_bf16 v[180:183], v[114:115], v[166:167], v[180:183]
	v_fma_f32 v168, v82, v172, -v142
	v_fma_f32 v169, v83, v173, -v143
	v_pk_mul_f32 v[142:143], v[82:83], v[146:147]
	s_nop 0
	v_mfma_f32_16x16x16_bf16 v[148:151], v[126:127], v[166:167], v[168:171]
	s_nop 2
	v_fma_f32 v170, v120, v174, v104
	v_fma_f32 v171, v121, v175, v105
	v_pk_fma_f32 v[168:169], v[94:95], v[172:173], v[142:143]
	v_pk_mul_f32 v[104:105], v[122:123], v[158:159]
	v_pk_mul_f32 v[142:143], v[98:99], v[156:157]
	v_pk_fma_f32 v[174:175], v[92:93], v[154:155], v[104:105] neg_lo:[0,0,1] neg_hi:[0,0,1]
	v_pk_fma_f32 v[172:173], v[84:85], v[152:153], v[142:143] neg_lo:[0,0,1] neg_hi:[0,0,1]
	v_pk_mul_f32 v[104:105], v[92:93], v[158:159]
	v_pk_mul_f32 v[142:143], v[84:85], v[156:157]
	v_pk_fma_f32 v[154:155], v[122:123], v[154:155], v[104:105]
	v_pk_fma_f32 v[152:153], v[98:99], v[152:153], v[142:143]
	v_pk_mul_f32 v[104:105], v[124:125], v[178:179]
	v_pk_mul_f32 v[142:143], v[100:101], v[176:177]
	v_pk_fma_f32 v[158:159], v[96:97], v[108:109], v[104:105] neg_lo:[0,0,1] neg_hi:[0,0,1]
	v_pk_fma_f32 v[156:157], v[90:91], v[106:107], v[142:143] neg_lo:[0,0,1] neg_hi:[0,0,1]
	v_pk_mul_f32 v[104:105], v[96:97], v[178:179]
	v_pk_mul_f32 v[142:143], v[90:91], v[176:177]
	v_pk_fma_f32 v[108:109], v[124:125], v[108:109], v[104:105]
	v_pk_fma_f32 v[106:107], v[100:101], v[106:107], v[142:143]
	v_mfma_f32_16x16x16_bf16 v[168:171], v[128:129], v[166:167], v[168:171]
	v_mul_f32_e64 v142, v88, v138
	v_mul_f32_e64 v143, v89, v139
	v_pk_mul_f32 v[138:139], v[78:79], v[138:139]
	v_pk_fma_f32 v[176:177], v[78:79], v[180:181], v[142:143] neg_lo:[0,0,1] neg_hi:[0,0,1]
	v_mfma_f32_16x16x16_bf16 v[172:175], v[130:131], v[166:167], v[172:175]
	v_mfma_f32_16x16x16_bf16 v[152:155], v[132:133], v[166:167], v[152:155]
	v_mfma_f32_16x16x16_bf16 v[156:159], v[134:135], v[166:167], v[156:159]
	v_mfma_f32_16x16x16_bf16 v[104:107], v[136:137], v[166:167], v[106:109]
	ds_read2_b64 v[164:167], v163 offset0:24 offset1:28
	s_nop 1
	v_pk_mul_f32 v[108:109], v[118:119], v[140:141]
	s_nop 0
	v_pk_fma_f32 v[178:179], v[80:81], v[182:183], v[108:109] neg_lo:[0,0,1] neg_hi:[0,0,1]
	v_pk_mul_f32 v[108:109], v[80:81], v[140:141]
	s_waitcnt lgkmcnt(0)
; #define LAS __attribute__((address_space(3)))
; #define S5_UPDATE(K, hre, him, xq) do { const v2u xb_ = (xq); \
;     _Pragma("unroll") for (int j = 0; j < 4; ++j) { const f32x4 cre_ = K.ar[j] * hre[j] - K.ai[j] * him[j], cim_ = K.ar[j] * him[j] + K.ai[j] * hre[j]; \
;         hre[j] = MFMA16K16(K.Bf[2 * j], xb_, cre_); him[j] = MFMA16K16(K.Bf[2 * j + 1], xb_, cim_); } } while (0)
; __device__ __forceinline__ void s5_prompt_task(const Args& a, const Ctx& C, int b, int g, v4u (&xv)[8]) {
;     ...
;     for (int t = 0; t < 16; ++t) { const v2u xq = *(const LAS v2u*)(xsl + t * 32); S5_UPDATE(K, hre, him, xq); }
	v_mfma_f32_16x16x16_bf16 v[140:143], v[114:115], v[164:165], v[176:179]
	s_nop 2
	v_fma_f32 v176, v88, v180, v138
	v_fma_f32 v177, v89, v181, v139
	v_pk_mul_f32 v[138:139], v[94:95], v[168:169]
	v_pk_fma_f32 v[178:179], v[118:119], v[182:183], v[108:109]
	v_pk_mul_f32 v[108:109], v[120:121], v[170:171]
	v_pk_fma_f32 v[180:181], v[82:83], v[148:149], v[138:139] neg_lo:[0,0,1] neg_hi:[0,0,1]
	v_pk_mul_f32 v[138:139], v[82:83], v[168:169]
	v_mfma_f32_16x16x16_bf16 v[176:179], v[116:117], v[164:165], v[176:179]
	v_fma_f32 v182, v86, v150, -v108
	v_fma_f32 v183, v87, v151, -v109
	v_pk_mul_f32 v[108:109], v[86:87], v[170:171]
	v_pk_fma_f32 v[148:149], v[94:95], v[148:149], v[138:139]
	v_pk_mul_f32 v[138:139], v[98:99], v[152:153]
	v_pk_fma_f32 v[150:151], v[120:121], v[150:151], v[108:109]
	v_pk_mul_f32 v[108:109], v[122:123], v[154:155]
	v_pk_fma_f32 v[168:169], v[84:85], v[172:173], v[138:139] neg_lo:[0,0,1] neg_hi:[0,0,1]
	v_pk_mul_f32 v[138:139], v[84:85], v[152:153]
	v_mfma_f32_16x16x16_bf16 v[146:149], v[128:129], v[164:165], v[148:151]
	v_fma_f32 v170, v92, v174, -v108
	v_fma_f32 v171, v93, v175, -v109
	v_pk_mul_f32 v[108:109], v[92:93], v[154:155]
	v_pk_fma_f32 v[150:151], v[98:99], v[172:173], v[138:139]
	v_pk_mul_f32 v[138:139], v[100:101], v[104:105]
	v_pk_fma_f32 v[152:153], v[122:123], v[174:175], v[108:109]
	v_pk_mul_f32 v[108:109], v[124:125], v[106:107]
	v_pk_fma_f32 v[172:173], v[90:91], v[156:157], v[138:139] neg_lo:[0,0,1] neg_hi:[0,0,1]
	v_pk_mul_f32 v[138:139], v[96:97], v[106:107]
	v_pk_mul_f32 v[104:105], v[90:91], v[104:105]
	v_mfma_f32_16x16x16_bf16 v[180:183], v[126:127], v[164:165], v[180:183]
	v_fma_f32 v174, v96, v158, -v108
	v_fma_f32 v175, v97, v159, -v109
	v_pk_fma_f32 v[158:159], v[124:125], v[158:159], v[138:139]
	v_pk_fma_f32 v[156:157], v[100:101], v[156:157], v[104:105]
	v_pk_mul_f32 v[104:105], v[118:119], v[178:179]
	v_pk_mul_f32 v[138:139], v[88:89], v[176:177]
	v_mfma_f32_16x16x16_bf16 v[150:153], v[132:133], v[164:165], v[150:153]
	v_mfma_f32_16x16x16_bf16 v[106:109], v[134:135], v[164:165], v[172:175]
	s_nop 2
	v_fma_f32 v174, v80, v142, -v104
	v_fma_f32 v175, v81, v143, -v105
	v_pk_fma_f32 v[172:173], v[78:79], v[140:141], v[138:139] neg_lo:[0,0,1] neg_hi:[0,0,1]
	v_pk_mul_f32 v[104:105], v[80:81], v[178:179]
	v_pk_mul_f32 v[138:139], v[78:79], v[176:177]
	v_mfma_f32_16x16x16_bf16 v[168:171], v[130:131], v[164:165], v[168:171]
	v_fma_f32 v142, v118, v142, v104
	v_fma_f32 v143, v119, v143, v105
	v_pk_fma_f32 v[140:141], v[88:89], v[140:141], v[138:139]
	v_pk_mul_f32 v[104:105], v[120:121], v[148:149]
	v_mfma_f32_16x16x16_bf16 v[154:157], v[136:137], v[164:165], v[156:159]
	v_fma_f32 v178, v86, v182, -v104
	v_fma_f32 v179, v87, v183, -v105
	v_pk_mul_f32 v[104:105], v[86:87], v[148:149]
	v_mfma_f32_16x16x16_bf16 v[138:141], v[116:117], v[166:167], v[140:143]
	v_fma_f32 v148, v120, v182, v104
	v_fma_f32 v149, v121, v183, v105
	v_pk_mul_f32 v[104:105], v[122:123], v[152:153]
	v_pk_mul_f32 v[142:143], v[94:95], v[146:147]
	v_pk_fma_f32 v[182:183], v[92:93], v[170:171], v[104:105] neg_lo:[0,0,1] neg_hi:[0,0,1]
	v_pk_fma_f32 v[176:177], v[82:83], v[180:181], v[142:143] neg_lo:[0,0,1] neg_hi:[0,0,1]
	v_pk_mul_f32 v[142:143], v[82:83], v[146:147]
	v_pk_mul_f32 v[104:105], v[92:93], v[152:153]
	v_pk_fma_f32 v[146:147], v[94:95], v[180:181], v[142:143]
	v_pk_mul_f32 v[142:143], v[98:99], v[150:151]
	v_pk_fma_f32 v[152:153], v[122:123], v[170:171], v[104:105]
	v_pk_fma_f32 v[180:181], v[84:85], v[168:169], v[142:143] neg_lo:[0,0,1] neg_hi:[0,0,1]
	v_pk_mul_f32 v[142:143], v[84:85], v[150:151]
	v_pk_mul_f32 v[104:105], v[124:125], v[156:157]
	v_pk_fma_f32 v[150:151], v[98:99], v[168:169], v[142:143]
	v_pk_mul_f32 v[142:143], v[100:101], v[154:155]
	v_pk_fma_f32 v[170:171], v[96:97], v[108:109], v[104:105] neg_lo:[0,0,1] neg_hi:[0,0,1]
	v_pk_fma_f32 v[168:169], v[90:91], v[106:107], v[142:143] neg_lo:[0,0,1] neg_hi:[0,0,1]
	v_pk_mul_f32 v[104:105], v[96:97], v[156:157]
	v_pk_mul_f32 v[142:143], v[90:91], v[154:155]
	v_pk_fma_f32 v[108:109], v[124:125], v[108:109], v[104:105]
	v_pk_fma_f32 v[106:107], v[100:101], v[106:107], v[142:143]
	v_mfma_f32_16x16x16_bf16 v[172:175], v[114:115], v[166:167], v[172:175]
	v_mul_f32_e64 v142, v88, v138
	v_mul_f32_e64 v143, v89, v139
	v_pk_mul_f32 v[138:139], v[78:79], v[138:139]
	v_mfma_f32_16x16x16_bf16 v[176:179], v[126:127], v[166:167], v[176:179]
	v_mfma_f32_16x16x16_bf16 v[146:149], v[128:129], v[166:167], v[146:149]
	v_mfma_f32_16x16x16_bf16 v[180:183], v[130:131], v[166:167], v[180:183]
	v_mfma_f32_16x16x16_bf16 v[150:153], v[132:133], v[166:167], v[150:153]
	v_mfma_f32_16x16x16_bf16 v[156:159], v[134:135], v[166:167], v[168:171]
	v_mfma_f32_16x16x16_bf16 v[104:107], v[136:137], v[166:167], v[106:109]
	ds_read2_b64 v[164:167], v163 offset0:32 offset1:36
	s_nop 0
	v_pk_fma_f32 v[168:169], v[78:79], v[172:173], v[142:143] neg_lo:[0,0,1] neg_hi:[0,0,1]
	v_pk_mul_f32 v[108:109], v[118:119], v[140:141]
	s_nop 0
	v_pk_fma_f32 v[170:171], v[80:81], v[174:175], v[108:109] neg_lo:[0,0,1] neg_hi:[0,0,1]
	v_pk_mul_f32 v[108:109], v[80:81], v[140:141]
	s_waitcnt lgkmcnt(0)
; #define LAS __attribute__((address_space(3)))
; #define S5_UPDATE(K, hre, him, xq) do { const v2u xb_ = (xq); \
;     _Pragma("unroll") for (int j = 0; j < 4; ++j) { const f32x4 cre_ = K.ar[j] * hre[j] - K.ai[j] * him[j], cim_ = K.ar[j] * him[j] + K.ai[j] * hre[j]; \
;         hre[j] = MFMA16K16(K.Bf[2 * j], xb_, cre_); him[j] = MFMA16K16(K.Bf[2 * j + 1], xb_, cim_); } } while (0)
; __device__ __forceinline__ void s5_prompt_task(const Args& a, const Ctx& C, int b, int g, v4u (&xv)[8]) {
;     ...
;     for (int t = 0; t < 16; ++t) { const v2u xq = *(const LAS v2u*)(xsl + t * 32); S5_UPDATE(K, hre, him, xq); }
	v_mfma_f32_16x16x16_bf16 v[140:143], v[114:115], v[164:165], v[168:171]
	s_nop 2
	v_fma_f32 v170, v118, v174, v108
	v_fma_f32 v171, v119, v175, v109
	v_pk_fma_f32 v[168:169], v[88:89], v[172:173], v[138:139]
	v_pk_mul_f32 v[108:109], v[120:121], v[148:149]
	v_pk_mul_f32 v[138:139], v[94:95], v[146:147]
	v_pk_fma_f32 v[174:175], v[86:87], v[178:179], v[108:109] neg_lo:[0,0,1] neg_hi:[0,0,1]
	v_pk_fma_f32 v[172:173], v[82:83], v[176:177], v[138:139] neg_lo:[0,0,1] neg_hi:[0,0,1]
	v_pk_mul_f32 v[108:109], v[86:87], v[148:149]
	v_pk_mul_f32 v[138:139], v[82:83], v[146:147]
	v_mfma_f32_16x16x16_bf16 v[168:171], v[116:117], v[164:165], v[168:171]
	v_fma_f32 v148, v120, v178, v108
	v_fma_f32 v149, v121, v179, v109
	v_pk_fma_f32 v[146:147], v[94:95], v[176:177], v[138:139]
	v_pk_mul_f32 v[108:109], v[122:123], v[152:153]
	v_pk_mul_f32 v[138:139], v[98:99], v[150:151]
	v_pk_fma_f32 v[178:179], v[92:93], v[182:183], v[108:109] neg_lo:[0,0,1] neg_hi:[0,0,1]
	v_pk_fma_f32 v[176:177], v[84:85], v[180:181], v[138:139] neg_lo:[0,0,1] neg_hi:[0,0,1]
	v_pk_mul_f32 v[138:139], v[84:85], v[150:151]
	v_pk_mul_f32 v[108:109], v[92:93], v[152:153]
	v_mfma_f32_16x16x16_bf16 v[152:155], v[130:131], v[164:165], v[176:179]
	s_nop 2
	v_fma_f32 v176, v98, v180, v138
	v_fma_f32 v177, v99, v181, v139
	v_pk_mul_f32 v[138:139], v[100:101], v[104:105]
	v_mfma_f32_16x16x16_bf16 v[146:149], v[128:129], v[164:165], v[146:149]
	v_fma_f32 v178, v122, v182, v108
	v_fma_f32 v179, v123, v183, v109
	v_pk_mul_f32 v[108:109], v[124:125], v[106:107]
	v_pk_fma_f32 v[180:181], v[90:91], v[156:157], v[138:139] neg_lo:[0,0,1] neg_hi:[0,0,1]
	v_pk_mul_f32 v[138:139], v[96:97], v[106:107]
	v_pk_mul_f32 v[104:105], v[90:91], v[104:105]
	v_mfma_f32_16x16x16_bf16 v[172:175], v[126:127], v[164:165], v[172:175]
	v_fma_f32 v182, v96, v158, -v108
	v_fma_f32 v183, v97, v159, -v109
	v_pk_fma_f32 v[158:159], v[124:125], v[158:159], v[138:139]
	v_pk_fma_f32 v[156:157], v[100:101], v[156:157], v[104:105]
	v_pk_mul_f32 v[104:105], v[118:119], v[170:171]
	v_pk_mul_f32 v[138:139], v[88:89], v[168:169]
	v_mfma_f32_16x16x16_bf16 v[176:179], v[132:133], v[164:165], v[176:179]
	v_mfma_f32_16x16x16_bf16 v[106:109], v[134:135], v[164:165], v[180:183]
	s_nop 2
	v_fma_f32 v182, v80, v142, -v104
	v_fma_f32 v183, v81, v143, -v105
	v_pk_fma_f32 v[180:181], v[78:79], v[140:141], v[138:139] neg_lo:[0,0,1] neg_hi:[0,0,1]
	v_pk_mul_f32 v[104:105], v[80:81], v[170:171]
	v_pk_mul_f32 v[138:139], v[78:79], v[168:169]
	v_pk_fma_f32 v[142:143], v[118:119], v[142:143], v[104:105]
	v_pk_fma_f32 v[140:141], v[88:89], v[140:141], v[138:139]
	v_mfma_f32_16x16x16_bf16 v[156:159], v[136:137], v[164:165], v[156:159]
	v_mul_f32_e64 v104, v120, v148
	v_mul_f32_e64 v105, v121, v149
	v_pk_fma_f32 v[170:171], v[86:87], v[174:175], v[104:105] neg_lo:[0,0,1] neg_hi:[0,0,1]
	v_mfma_f32_16x16x16_bf16 v[138:141], v[116:117], v[166:167], v[140:143]
	v_mul_f32_e64 v104, v86, v148
	v_mul_f32_e64 v105, v87, v149
	s_nop 0
	v_pk_mul_f32 v[142:143], v[94:95], v[146:147]
	v_mfma_f32_16x16x16_bf16 v[180:183], v[114:115], v[166:167], v[180:183]
	v_fma_f32 v168, v82, v172, -v142
	v_fma_f32 v169, v83, v173, -v143
	v_pk_mul_f32 v[142:143], v[82:83], v[146:147]
	s_nop 0
	v_mfma_f32_16x16x16_bf16 v[148:151], v[126:127], v[166:167], v[168:171]
	s_nop 2
	v_fma_f32 v170, v120, v174, v104
	v_fma_f32 v171, v121, v175, v105
	v_pk_fma_f32 v[168:169], v[94:95], v[172:173], v[142:143]
	v_pk_mul_f32 v[104:105], v[122:123], v[178:179]
	v_pk_mul_f32 v[142:143], v[98:99], v[176:177]
	v_pk_fma_f32 v[174:175], v[92:93], v[154:155], v[104:105] neg_lo:[0,0,1] neg_hi:[0,0,1]
	v_pk_fma_f32 v[172:173], v[84:85], v[152:153], v[142:143] neg_lo:[0,0,1] neg_hi:[0,0,1]
	v_pk_mul_f32 v[104:105], v[92:93], v[178:179]
	v_pk_mul_f32 v[142:143], v[84:85], v[176:177]
	v_pk_fma_f32 v[154:155], v[122:123], v[154:155], v[104:105]
	v_pk_fma_f32 v[152:153], v[98:99], v[152:153], v[142:143]
	v_pk_mul_f32 v[104:105], v[124:125], v[158:159]
	v_pk_mul_f32 v[142:143], v[100:101], v[156:157]
	v_pk_fma_f32 v[178:179], v[96:97], v[108:109], v[104:105] neg_lo:[0,0,1] neg_hi:[0,0,1]
	v_pk_fma_f32 v[176:177], v[90:91], v[106:107], v[142:143] neg_lo:[0,0,1] neg_hi:[0,0,1]
	v_pk_mul_f32 v[104:105], v[96:97], v[158:159]
	v_pk_mul_f32 v[142:143], v[90:91], v[156:157]
	ds_read2_b64 v[156:159], v163 offset0:40 offset1:44
	v_mfma_f32_16x16x16_bf16 v[168:171], v[128:129], v[166:167], v[168:171]
	v_fma_f32 v108, v124, v108, v104
	v_fma_f32 v109, v125, v109, v105
	v_pk_fma_f32 v[106:107], v[100:101], v[106:107], v[142:143]
	v_pk_mul_f32 v[142:143], v[88:89], v[138:139]
	v_mfma_f32_16x16x16_bf16 v[152:155], v[132:133], v[166:167], v[152:155]
	v_fma_f32 v164, v78, v180, -v142
	v_fma_f32 v165, v79, v181, -v143
	v_pk_mul_f32 v[138:139], v[78:79], v[138:139]
	v_mfma_f32_16x16x16_bf16 v[104:107], v[136:137], v[166:167], v[106:109]
	s_nop 2
	v_mul_f32_e64 v108, v118, v140
	v_mul_f32_e64 v109, v119, v141
	v_mfma_f32_16x16x16_bf16 v[172:175], v[130:131], v[166:167], v[172:175]
	v_mfma_f32_16x16x16_bf16 v[176:179], v[134:135], v[166:167], v[176:179]
	v_fma_f32 v166, v80, v182, -v108
	v_fma_f32 v167, v81, v183, -v109
	v_pk_mul_f32 v[108:109], v[80:81], v[140:141]
	s_waitcnt lgkmcnt(0)
; #define LAS __attribute__((address_space(3)))
; #define S5_UPDATE(K, hre, him, xq) do { const v2u xb_ = (xq); \
;     _Pragma("unroll") for (int j = 0; j < 4; ++j) { const f32x4 cre_ = K.ar[j] * hre[j] - K.ai[j] * him[j], cim_ = K.ar[j] * him[j] + K.ai[j] * hre[j]; \
;         hre[j] = MFMA16K16(K.Bf[2 * j], xb_, cre_); him[j] = MFMA16K16(K.Bf[2 * j + 1], xb_, cim_); } } while (0)
; __device__ __forceinline__ void s5_prompt_task(const Args& a, const Ctx& C, int b, int g, v4u (&xv)[8]) {
;     ...
;     for (int t = 0; t < 16; ++t) { const v2u xq = *(const LAS v2u*)(xsl + t * 32); S5_UPDATE(K, hre, him, xq); }
	v_mfma_f32_16x16x16_bf16 v[140:143], v[114:115], v[156:157], v[164:167]
	s_nop 2
	v_fma_f32 v166, v118, v182, v108
	v_fma_f32 v167, v119, v183, v109
	v_pk_fma_f32 v[164:165], v[88:89], v[180:181], v[138:139]
	v_pk_mul_f32 v[108:109], v[120:121], v[170:171]
	v_pk_mul_f32 v[138:139], v[94:95], v[168:169]
	v_pk_fma_f32 v[182:183], v[86:87], v[150:151], v[108:109] neg_lo:[0,0,1] neg_hi:[0,0,1]
	v_pk_fma_f32 v[180:181], v[82:83], v[148:149], v[138:139] neg_lo:[0,0,1] neg_hi:[0,0,1]
	v_pk_mul_f32 v[108:109], v[86:87], v[170:171]
	v_pk_mul_f32 v[138:139], v[82:83], v[168:169]
	v_mfma_f32_16x16x16_bf16 v[164:167], v[116:117], v[156:157], v[164:167]
	v_fma_f32 v150, v120, v150, v108
	v_fma_f32 v151, v121, v151, v109
	v_pk_fma_f32 v[148:149], v[94:95], v[148:149], v[138:139]
	v_pk_mul_f32 v[108:109], v[122:123], v[154:155]
	v_pk_mul_f32 v[138:139], v[98:99], v[152:153]
	v_pk_fma_f32 v[170:171], v[92:93], v[174:175], v[108:109] neg_lo:[0,0,1] neg_hi:[0,0,1]
	v_pk_fma_f32 v[168:169], v[84:85], v[172:173], v[138:139] neg_lo:[0,0,1] neg_hi:[0,0,1]
	v_pk_mul_f32 v[108:109], v[92:93], v[154:155]
	v_pk_mul_f32 v[138:139], v[84:85], v[152:153]
	v_mfma_f32_16x16x16_bf16 v[146:149], v[128:129], v[156:157], v[148:151]
	v_fma_f32 v152, v122, v174, v108
	v_fma_f32 v153, v123, v175, v109
	v_pk_mul_f32 v[108:109], v[124:125], v[106:107]
	v_pk_fma_f32 v[150:151], v[98:99], v[172:173], v[138:139]
	v_pk_mul_f32 v[138:139], v[100:101], v[104:105]
	v_pk_fma_f32 v[174:175], v[96:97], v[178:179], v[108:109] neg_lo:[0,0,1] neg_hi:[0,0,1]
	v_pk_fma_f32 v[172:173], v[90:91], v[176:177], v[138:139] neg_lo:[0,0,1] neg_hi:[0,0,1]
	v_pk_mul_f32 v[138:139], v[96:97], v[106:107]
	v_pk_mul_f32 v[104:105], v[90:91], v[104:105]
	v_mfma_f32_16x16x16_bf16 v[180:183], v[126:127], v[156:157], v[180:183]
	v_mfma_f32_16x16x16_bf16 v[106:109], v[134:135], v[156:157], v[172:175]
	s_nop 2
	v_fma_f32 v174, v124, v178, v138
	v_fma_f32 v175, v125, v179, v139
	v_pk_fma_f32 v[172:173], v[100:101], v[176:177], v[104:105]
	v_pk_mul_f32 v[104:105], v[118:119], v[166:167]
	v_pk_mul_f32 v[138:139], v[88:89], v[164:165]
	v_mfma_f32_16x16x16_bf16 v[168:171], v[130:131], v[156:157], v[168:171]
	v_mfma_f32_16x16x16_bf16 v[150:153], v[132:133], v[156:157], v[150:153]
	v_mfma_f32_16x16x16_bf16 v[154:157], v[136:137], v[156:157], v[172:175]
	s_nop 2
	v_fma_f32 v174, v80, v142, -v104
	v_fma_f32 v175, v81, v143, -v105
	v_pk_fma_f32 v[172:173], v[78:79], v[140:141], v[138:139] neg_lo:[0,0,1] neg_hi:[0,0,1]
	v_pk_mul_f32 v[104:105], v[80:81], v[166:167]
	v_pk_mul_f32 v[138:139], v[78:79], v[164:165]
	v_pk_fma_f32 v[142:143], v[118:119], v[142:143], v[104:105]
	v_pk_fma_f32 v[140:141], v[88:89], v[140:141], v[138:139]
	v_pk_mul_f32 v[104:105], v[120:121], v[148:149]
	v_mfma_f32_16x16x16_bf16 v[172:175], v[114:115], v[158:159], v[172:175]
	v_fma_f32 v166, v86, v182, -v104
	v_fma_f32 v167, v87, v183, -v105
	v_pk_mul_f32 v[104:105], v[86:87], v[148:149]
	v_mfma_f32_16x16x16_bf16 v[138:141], v[116:117], v[158:159], v[140:143]
	v_fma_f32 v148, v120, v182, v104
	v_fma_f32 v149, v121, v183, v105
	v_pk_mul_f32 v[104:105], v[122:123], v[152:153]
	v_pk_mul_f32 v[142:143], v[94:95], v[146:147]
	v_pk_fma_f32 v[178:179], v[92:93], v[170:171], v[104:105] neg_lo:[0,0,1] neg_hi:[0,0,1]
	v_pk_fma_f32 v[164:165], v[82:83], v[180:181], v[142:143] neg_lo:[0,0,1] neg_hi:[0,0,1]
	v_pk_mul_f32 v[142:143], v[82:83], v[146:147]
	v_pk_mul_f32 v[104:105], v[92:93], v[152:153]
	v_pk_fma_f32 v[146:147], v[94:95], v[180:181], v[142:143]
	v_pk_mul_f32 v[142:143], v[98:99], v[150:151]
	v_pk_fma_f32 v[152:153], v[122:123], v[170:171], v[104:105]
	v_pk_fma_f32 v[176:177], v[84:85], v[168:169], v[142:143] neg_lo:[0,0,1] neg_hi:[0,0,1]
	v_pk_mul_f32 v[142:143], v[84:85], v[150:151]
	v_pk_mul_f32 v[104:105], v[124:125], v[156:157]
	v_pk_fma_f32 v[150:151], v[98:99], v[168:169], v[142:143]
	v_pk_mul_f32 v[142:143], v[100:101], v[154:155]
	v_mfma_f32_16x16x16_bf16 v[146:149], v[128:129], v[158:159], v[146:149]
	v_fma_f32 v170, v96, v108, -v104
	v_fma_f32 v171, v97, v109, -v105
	v_pk_fma_f32 v[168:169], v[90:91], v[106:107], v[142:143] neg_lo:[0,0,1] neg_hi:[0,0,1]
	v_pk_mul_f32 v[104:105], v[96:97], v[156:157]
	v_pk_mul_f32 v[142:143], v[90:91], v[154:155]
	ds_read2_b64 v[154:157], v163 offset0:48 offset1:52
	v_mfma_f32_16x16x16_bf16 v[164:167], v[126:127], v[158:159], v[164:167]
	v_fma_f32 v108, v124, v108, v104
	v_fma_f32 v109, v125, v109, v105
	v_pk_fma_f32 v[106:107], v[100:101], v[106:107], v[142:143]
	v_pk_mul_f32 v[142:143], v[88:89], v[138:139]
	v_mfma_f32_16x16x16_bf16 v[150:153], v[132:133], v[158:159], v[150:153]
	v_mul_f32_e64 v138, v78, v138
	v_mul_f32_e64 v139, v79, v139
	v_pk_fma_f32 v[180:181], v[78:79], v[172:173], v[142:143] neg_lo:[0,0,1] neg_hi:[0,0,1]
	v_pk_fma_f32 v[172:173], v[88:89], v[172:173], v[138:139]
	v_mfma_f32_16x16x16_bf16 v[176:179], v[130:131], v[158:159], v[176:179]
	v_mul_f32_e64 v138, v94, v146
	v_mul_f32_e64 v139, v95, v147
	v_mfma_f32_16x16x16_bf16 v[104:107], v[136:137], v[158:159], v[106:109]
	s_nop 2
	v_mul_f32_e64 v108, v118, v140
	v_mul_f32_e64 v109, v119, v141
	v_mfma_f32_16x16x16_bf16 v[168:171], v[134:135], v[158:159], v[168:171]
	v_fma_f32 v182, v80, v174, -v108
	v_fma_f32 v183, v81, v175, -v109
	v_pk_mul_f32 v[108:109], v[80:81], v[140:141]
	s_waitcnt lgkmcnt(0)
; #define LAS __attribute__((address_space(3)))
; #define S5_UPDATE(K, hre, him, xq) do { const v2u xb_ = (xq); \
;     _Pragma("unroll") for (int j = 0; j < 4; ++j) { const f32x4 cre_ = K.ar[j] * hre[j] - K.ai[j] * him[j], cim_ = K.ar[j] * him[j] + K.ai[j] * hre[j]; \
;         hre[j] = MFMA16K16(K.Bf[2 * j], xb_, cre_); him[j] = MFMA16K16(K.Bf[2 * j + 1], xb_, cim_); } } while (0)
; __device__ __forceinline__ void s5_prompt_task(const Args& a, const Ctx& C, int b, int g, v4u (&xv)[8]) {
;     ...
;     for (int t = 0; t < 16; ++t) { const v2u xq = *(const LAS v2u*)(xsl + t * 32); S5_UPDATE(K, hre, him, xq); }
	v_mfma_f32_16x16x16_bf16 v[140:143], v[114:115], v[154:155], v[180:183]
	v_fma_f32 v174, v118, v174, v108
	v_fma_f32 v175, v119, v175, v109
	v_pk_mul_f32 v[108:109], v[120:121], v[148:149]
	v_pk_fma_f32 v[180:181], v[82:83], v[164:165], v[138:139] neg_lo:[0,0,1] neg_hi:[0,0,1]
	v_pk_mul_f32 v[138:139], v[82:83], v[146:147]
	v_mfma_f32_16x16x16_bf16 v[172:175], v[116:117], v[154:155], v[172:175]
	v_fma_f32 v182, v86, v166, -v108
	v_fma_f32 v183, v87, v167, -v109
	v_pk_mul_f32 v[108:109], v[86:87], v[148:149]
	v_pk_fma_f32 v[146:147], v[94:95], v[164:165], v[138:139]
	v_pk_mul_f32 v[138:139], v[98:99], v[150:151]
	v_pk_fma_f32 v[148:149], v[120:121], v[166:167], v[108:109]
	v_pk_mul_f32 v[108:109], v[122:123], v[152:153]
	v_pk_fma_f32 v[164:165], v[84:85], v[176:177], v[138:139] neg_lo:[0,0,1] neg_hi:[0,0,1]
	v_pk_mul_f32 v[138:139], v[84:85], v[150:151]
	v_pk_fma_f32 v[166:167], v[92:93], v[178:179], v[108:109] neg_lo:[0,0,1] neg_hi:[0,0,1]
	v_pk_mul_f32 v[108:109], v[92:93], v[152:153]
	v_pk_fma_f32 v[150:151], v[98:99], v[176:177], v[138:139]
	v_pk_mul_f32 v[138:139], v[100:101], v[104:105]
	v_mfma_f32_16x16x16_bf16 v[146:149], v[128:129], v[154:155], v[146:149]
	v_fma_f32 v152, v122, v178, v108
	v_fma_f32 v153, v123, v179, v109
	v_pk_mul_f32 v[108:109], v[124:125], v[106:107]
	v_pk_fma_f32 v[176:177], v[90:91], v[168:169], v[138:139] neg_lo:[0,0,1] neg_hi:[0,0,1]
	v_pk_mul_f32 v[138:139], v[96:97], v[106:107]
	v_pk_mul_f32 v[104:105], v[90:91], v[104:105]
	v_mfma_f32_16x16x16_bf16 v[180:183], v[126:127], v[154:155], v[180:183]
	v_fma_f32 v178, v96, v170, -v108
	v_fma_f32 v179, v97, v171, -v109
	v_pk_fma_f32 v[170:171], v[124:125], v[170:171], v[138:139]
	v_pk_fma_f32 v[168:169], v[100:101], v[168:169], v[104:105]
	v_pk_mul_f32 v[104:105], v[118:119], v[174:175]
	v_pk_mul_f32 v[138:139], v[88:89], v[172:173]
	v_mfma_f32_16x16x16_bf16 v[150:153], v[132:133], v[154:155], v[150:153]
	v_mfma_f32_16x16x16_bf16 v[106:109], v[134:135], v[154:155], v[176:179]
	s_nop 2
	v_fma_f32 v178, v80, v142, -v104
	v_fma_f32 v179, v81, v143, -v105
	v_pk_fma_f32 v[176:177], v[78:79], v[140:141], v[138:139] neg_lo:[0,0,1] neg_hi:[0,0,1]
	v_pk_mul_f32 v[104:105], v[80:81], v[174:175]
	v_pk_mul_f32 v[138:139], v[78:79], v[172:173]
	v_mfma_f32_16x16x16_bf16 v[164:167], v[130:131], v[154:155], v[164:167]
	v_fma_f32 v142, v118, v142, v104
	v_fma_f32 v143, v119, v143, v105
	v_pk_fma_f32 v[140:141], v[88:89], v[140:141], v[138:139]
	v_pk_mul_f32 v[104:105], v[120:121], v[148:149]
	v_mfma_f32_16x16x16_bf16 v[168:171], v[136:137], v[154:155], v[168:171]
	v_fma_f32 v186, v86, v182, -v104
	v_fma_f32 v187, v87, v183, -v105
	v_pk_mul_f32 v[104:105], v[86:87], v[148:149]
	v_mfma_f32_16x16x16_bf16 v[138:141], v[116:117], v[156:157], v[140:143]
	v_fma_f32 v148, v120, v182, v104
	v_fma_f32 v149, v121, v183, v105
	v_pk_mul_f32 v[104:105], v[122:123], v[152:153]
	v_pk_mul_f32 v[142:143], v[94:95], v[146:147]
	v_mfma_f32_16x16x16_bf16 v[174:177], v[114:115], v[156:157], v[176:179]
	v_fma_f32 v184, v82, v180, -v142
	v_fma_f32 v185, v83, v181, -v143
	v_pk_mul_f32 v[142:143], v[82:83], v[146:147]
	s_nop 0
	v_pk_fma_f32 v[146:147], v[94:95], v[180:181], v[142:143]
	v_pk_mul_f32 v[142:143], v[98:99], v[150:151]
	v_pk_fma_f32 v[180:181], v[92:93], v[166:167], v[104:105] neg_lo:[0,0,1] neg_hi:[0,0,1]
	v_pk_fma_f32 v[178:179], v[84:85], v[164:165], v[142:143] neg_lo:[0,0,1] neg_hi:[0,0,1]
	v_pk_mul_f32 v[104:105], v[92:93], v[152:153]
	v_pk_mul_f32 v[142:143], v[84:85], v[150:151]
	v_pk_fma_f32 v[166:167], v[122:123], v[166:167], v[104:105]
	v_pk_fma_f32 v[164:165], v[98:99], v[164:165], v[142:143]
	v_pk_mul_f32 v[104:105], v[124:125], v[170:171]
	v_pk_mul_f32 v[142:143], v[100:101], v[168:169]
	v_mfma_f32_16x16x16_bf16 v[152:155], v[130:131], v[156:157], v[178:181]
	s_nop 2
	v_fma_f32 v180, v96, v108, -v104
	v_fma_f32 v181, v97, v109, -v105
	v_pk_fma_f32 v[178:179], v[90:91], v[106:107], v[142:143] neg_lo:[0,0,1] neg_hi:[0,0,1]
	v_pk_mul_f32 v[104:105], v[96:97], v[170:171]
	v_pk_mul_f32 v[142:143], v[90:91], v[168:169]
	v_pk_fma_f32 v[108:109], v[124:125], v[108:109], v[104:105]
	v_pk_fma_f32 v[106:107], v[100:101], v[106:107], v[142:143]
	v_mfma_f32_16x16x16_bf16 v[184:187], v[126:127], v[156:157], v[184:187]
	v_mul_f32_e64 v142, v88, v138
	v_mul_f32_e64 v143, v89, v139
	v_pk_mul_f32 v[138:139], v[78:79], v[138:139]
	v_mfma_f32_16x16x16_bf16 v[146:149], v[128:129], v[156:157], v[146:149]
	v_mfma_f32_16x16x16_bf16 v[164:167], v[132:133], v[156:157], v[164:167]
	v_mfma_f32_16x16x16_bf16 v[170:173], v[134:135], v[156:157], v[178:181]
	v_mfma_f32_16x16x16_bf16 v[104:107], v[136:137], v[156:157], v[106:109]
	ds_read2_b64 v[156:159], v163 offset0:56 offset1:60
	s_nop 0
	v_pk_fma_f32 v[178:179], v[78:79], v[174:175], v[142:143] neg_lo:[0,0,1] neg_hi:[0,0,1]
	v_pk_fma_f32 v[174:175], v[88:89], v[174:175], v[138:139]
	v_pk_mul_f32 v[108:109], v[118:119], v[140:141]
	v_pk_mul_f32 v[138:139], v[94:95], v[146:147]
	v_pk_fma_f32 v[180:181], v[80:81], v[176:177], v[108:109] neg_lo:[0,0,1] neg_hi:[0,0,1]
	v_pk_mul_f32 v[108:109], v[80:81], v[140:141]
	s_nop 0
	v_pk_fma_f32 v[176:177], v[118:119], v[176:177], v[108:109]
	v_pk_mul_f32 v[108:109], v[120:121], v[148:149]
	s_waitcnt lgkmcnt(0)
; #define LAS __attribute__((address_space(3)))
; #define S5_UPDATE(K, hre, him, xq) do { const v2u xb_ = (xq); \
;     _Pragma("unroll") for (int j = 0; j < 4; ++j) { const f32x4 cre_ = K.ar[j] * hre[j] - K.ai[j] * him[j], cim_ = K.ar[j] * him[j] + K.ai[j] * hre[j]; \
;         hre[j] = MFMA16K16(K.Bf[2 * j], xb_, cre_); him[j] = MFMA16K16(K.Bf[2 * j + 1], xb_, cim_); } } while (0)
; __device__ __forceinline__ void s5_prompt_task(const Args& a, const Ctx& C, int b, int g, v4u (&xv)[8]) {
;     ...
;     for (int t = 0; t < 16; ++t) { const v2u xq = *(const LAS v2u*)(xsl + t * 32); S5_UPDATE(K, hre, him, xq); }
; #pragma unroll
;     for (int j = 0; j < 4; ++j) { LAS float* d = SH + chunk * 132 + 2 * (16 * j + 4 * q);
;         *(LAS f32x4*)d = (f32x4){hre[j][0], him[j][0], hre[j][1], him[j][1]}; *(LAS f32x4*)(d + 4) = (f32x4){hre[j][2], him[j][2], hre[j][3], him[j][3]}; }
	v_mfma_f32_16x16x16_bf16 v[140:143], v[114:115], v[156:157], v[178:181]
	s_nop 2
	v_fma_f32 v180, v86, v186, -v108
	v_fma_f32 v181, v87, v187, -v109
	v_pk_fma_f32 v[178:179], v[82:83], v[184:185], v[138:139] neg_lo:[0,0,1] neg_hi:[0,0,1]
	v_pk_mul_f32 v[138:139], v[82:83], v[146:147]
	v_mfma_f32_16x16x16_bf16 v[174:177], v[116:117], v[156:157], v[174:177]
	v_mul_f32_e64 v108, v86, v148
	v_mul_f32_e64 v109, v87, v149
	v_mfma_f32_16x16x16_bf16 v[148:151], v[126:127], v[156:157], v[178:181]
	s_nop 2
	v_fma_f32 v178, v94, v184, v138
	v_fma_f32 v179, v95, v185, v139
	v_pk_mul_f32 v[138:139], v[98:99], v[164:165]
	v_pk_fma_f32 v[180:181], v[120:121], v[186:187], v[108:109]
	v_pk_mul_f32 v[108:109], v[122:123], v[166:167]
	v_pk_fma_f32 v[182:183], v[84:85], v[152:153], v[138:139] neg_lo:[0,0,1] neg_hi:[0,0,1]
	v_pk_mul_f32 v[138:139], v[84:85], v[164:165]
	v_mfma_f32_16x16x16_bf16 v[178:181], v[128:129], v[156:157], v[178:181]
	v_fma_f32 v184, v92, v154, -v108
	v_fma_f32 v185, v93, v155, -v109
	v_pk_mul_f32 v[108:109], v[92:93], v[166:167]
	v_pk_fma_f32 v[152:153], v[98:99], v[152:153], v[138:139]
	v_pk_mul_f32 v[138:139], v[100:101], v[104:105]
	v_mfma_f32_16x16x16_bf16 v[166:169], v[130:131], v[156:157], v[182:185]
	v_fma_f32 v154, v122, v154, v108
	v_fma_f32 v155, v123, v155, v109
	v_pk_mul_f32 v[108:109], v[124:125], v[106:107]
	v_pk_mul_f32 v[104:105], v[90:91], v[104:105]
	v_pk_fma_f32 v[182:183], v[90:91], v[170:171], v[138:139] neg_lo:[0,0,1] neg_hi:[0,0,1]
	v_pk_mul_f32 v[138:139], v[96:97], v[106:107]
	v_mfma_f32_16x16x16_bf16 v[152:155], v[132:133], v[156:157], v[152:155]
	v_fma_f32 v184, v96, v172, -v108
	v_fma_f32 v185, v97, v173, -v109
	v_pk_fma_f32 v[172:173], v[124:125], v[172:173], v[138:139]
	v_pk_mul_f32 v[138:139], v[88:89], v[174:175]
	v_mfma_f32_16x16x16_bf16 v[106:109], v[134:135], v[156:157], v[182:185]
	v_fma_f32 v170, v100, v170, v104
	v_fma_f32 v171, v101, v171, v105
	v_pk_mul_f32 v[104:105], v[118:119], v[176:177]
	v_pk_fma_f32 v[182:183], v[78:79], v[140:141], v[138:139] neg_lo:[0,0,1] neg_hi:[0,0,1]
	v_pk_mul_f32 v[78:79], v[78:79], v[174:175]
	v_mfma_f32_16x16x16_bf16 v[170:173], v[136:137], v[156:157], v[170:173]
	v_fma_f32 v184, v80, v142, -v104
	v_fma_f32 v185, v81, v143, -v105
	v_pk_fma_f32 v[78:79], v[88:89], v[140:141], v[78:79]
	v_pk_mul_f32 v[88:89], v[120:121], v[180:181]
	v_pk_mul_f32 v[104:105], v[94:95], v[178:179]
	v_pk_fma_f32 v[140:141], v[86:87], v[150:151], v[88:89] neg_lo:[0,0,1] neg_hi:[0,0,1]
	v_pk_fma_f32 v[138:139], v[82:83], v[148:149], v[104:105] neg_lo:[0,0,1] neg_hi:[0,0,1]
	v_pk_mul_f32 v[82:83], v[82:83], v[178:179]
	v_pk_mul_f32 v[80:81], v[80:81], v[176:177]
	v_pk_mul_f32 v[104:105], v[86:87], v[180:181]
	v_mfma_f32_16x16x16_bf16 v[86:89], v[126:127], v[158:159], v[138:141]
	v_fma_f32 v80, v118, v142, v80
	v_fma_f32 v81, v119, v143, v81
	s_nop 0
	v_pk_fma_f32 v[138:139], v[94:95], v[148:149], v[82:83]
	v_pk_mul_f32 v[82:83], v[122:123], v[154:155]
	v_pk_fma_f32 v[140:141], v[120:121], v[150:151], v[104:105]
	v_pk_mul_f32 v[94:95], v[98:99], v[152:153]
	v_pk_fma_f32 v[148:149], v[92:93], v[168:169], v[82:83] neg_lo:[0,0,1] neg_hi:[0,0,1]
	v_pk_mul_f32 v[82:83], v[92:93], v[154:155]
	v_pk_mul_f32 v[104:105], v[84:85], v[152:153]
	v_mfma_f32_16x16x16_bf16 v[182:185], v[114:115], v[158:159], v[182:185]
	v_fma_f32 v146, v84, v166, -v94
	v_fma_f32 v147, v85, v167, -v95
	v_pk_fma_f32 v[84:85], v[122:123], v[168:169], v[82:83]
	v_pk_fma_f32 v[82:83], v[98:99], v[166:167], v[104:105]
	v_mfma_f32_16x16x16_bf16 v[78:81], v[116:117], v[158:159], v[78:81]
	v_mul_f32_e64 v104, v100, v170
	v_mul_f32_e64 v105, v101, v171
	v_pk_mul_f32 v[98:99], v[124:125], v[172:173]
	v_mov_b32_e32 v102, v183
	v_mfma_f32_16x16x16_bf16 v[138:141], v[128:129], v[158:159], v[138:141]
	v_lshlrev_b32_e32 v152, 3, v162
	s_nop 1
	v_mov_b32_e32 v103, v79
	v_mov_b32_e32 v79, v80
	v_mfma_f32_16x16x16_bf16 v[92:95], v[130:131], v[158:159], v[146:149]
	v_mov_b32_e32 v80, v185
	v_mov_b32_e32 v153, v111
	s_nop 0
	v_pk_fma_f32 v[146:147], v[90:91], v[106:107], v[104:105] neg_lo:[0,0,1] neg_hi:[0,0,1]
	v_pk_mul_f32 v[104:105], v[96:97], v[172:173]
	v_pk_mul_f32 v[90:91], v[90:91], v[170:171]
	v_mfma_f32_16x16x16_bf16 v[82:85], v[132:133], v[158:159], v[82:85]
	v_fma_f32 v148, v96, v108, -v98
	v_fma_f32 v149, v97, v109, -v99
	v_pk_fma_f32 v[108:109], v[124:125], v[108:109], v[104:105]
	v_pk_fma_f32 v[106:107], v[100:101], v[106:107], v[90:91]
	v_mfma_f32_16x16x16_bf16 v[96:99], v[134:135], v[158:159], v[146:149]
	v_mov_b32_e32 v101, v78
	v_mov_b32_e32 v78, v184
	ds_write_b128 v3, v[78:81] offset:16
	v_mfma_f32_16x16x16_bf16 v[104:107], v[136:137], v[158:159], v[106:109]
	v_mov_b32_e32 v78, v86
	v_mov_b32_e32 v79, v138
	v_mov_b32_e32 v80, v87
	v_mov_b32_e32 v81, v139
	ds_write_b128 v3, v[78:81] offset:128
	v_mov_b32_e32 v78, v92
	v_mov_b32_e32 v79, v82
	v_mov_b32_e32 v80, v93
	v_mov_b32_e32 v81, v83
	ds_write_b128 v3, v[78:81] offset:256
	v_mov_b32_e32 v78, v96
	v_mov_b32_e32 v79, v104
	v_mov_b32_e32 v80, v97
	v_mov_b32_e32 v81, v105
	v_mov_b32_e32 v138, v88
	v_mov_b32_e32 v139, v140
	v_mov_b32_e32 v140, v89
	v_mov_b32_e32 v82, v94
	v_mov_b32_e32 v83, v84
	v_mov_b32_e32 v84, v95
	ds_write_b128 v3, v[78:81] offset:384
	v_lshl_add_u64 v[78:79], s[4:5], 0, v[110:111]
	s_mov_b64 s[4:5], 0xd400000
	v_mov_b32_e32 v110, v7
	v_mov_b32_e32 v100, v182
	ds_write_b128 v3, v[138:141] offset:144
	ds_write_b128 v3, v[82:85] offset:272
	v_mov_b32_e32 v104, v98
	v_mov_b32_e32 v105, v106
	v_mov_b32_e32 v106, v99
	v_lshl_add_u64 v[138:139], v[78:79], 0, s[4:5]
	v_lshlrev_b64 v[78:79], 5, v[110:111]
	v_or_b32_e32 v80, 1, v7
	v_mov_b32_e32 v81, v111
; #define LAS __attribute__((address_space(3)))
; #define LDS_WAIT() asm volatile("s_waitcnt lgkmcnt(0)" ::: "memory")
; __device__ __forceinline__ unsigned pk2(float lo, float hi) { return pg8::cvt_pk_bf16(lo, hi); }
; __device__ __forceinline__ bf16x8 pack8(f32x4 lo, f32x4 hi) { v4u w; w.x = pk2(lo[0], lo[1]); w.y = pk2(lo[2], lo[3]); w.z = pk2(hi[0], hi[1]); w.w = pk2(hi[2], hi[3]); return __builtin_bit_cast(bf16x8, w); }
; __device__ __forceinline__ void s5_load_consts(S5C& K, const Args& a, int g, int lane) {
;     ...
;     const float* cre = a.in[I_CRE] + ((size_t)g * 16 + fr) * 64; const float* cim = a.in[I_CIM] + ((size_t)g * 16 + fr) * 64;
; #pragma unroll
;     for (int j = 0; j < 4; ++j) { const f32x4 r4 = *(const f32x4*)(cre + 16 * j + 4 * q), i4 = *(const f32x4*)(cim + 16 * j + 4 * q); K.Cf[j] = pack8(r4, -i4); }
;     const float* wg = a.in[I_WGLU] + (size_t)g * 512;
;     { f32x4 v, gt;
; #pragma unroll
;       for (int e = 0; e < 4; ++e) { v[e] = wg[(4 * q + e) * 32 + fr]; gt[e] = wg[(4 * q + e) * 32 + 16 + fr]; }
;       K.Wv = (v2u){pk2(v[0], v[1]), pk2(v[2], v[3])}; K.Wg = (v2u){pk2(gt[0], gt[1]), pk2(gt[2], gt[3])}; }
;     K.dsk = *(const f32x4*)(a.in[I_DSKIP] + g * 16 + 4 * q);
;     K.bv = *(const f32x4*)(a.in[I_BGLU] + g * 32 + 4 * q); K.bg = *(const f32x4*)(a.in[I_BGLU] + g * 32 + 16 + 4 * q);
; __device__ __forceinline__ void s5_prompt_task(const Args& a, const Ctx& C, int b, int g, v4u (&xv)[8]) {
;     ...
;     v2u zq[4];
; #pragma unroll
;     for (int t = 0; t < 4; ++t) zq[t] = __builtin_nontemporal_load((const v2u*)(ZBg + (size_t)(16 * chunk + t) * 16 + 4 * q));
;     LDS_WAIT();
;     { const float* A16 = (const float*)(a.ws + WS_S5C + S5C_A16) + (size_t)g * 128; const float* A256 = (const float*)(a.ws + WS_S5C + S5C_A256) + (size_t)g * 128;
;       const float a16r = A16[2 * lane], a16i = A16[2 * lane + 1], a256r = A256[2 * lane], a256i = A256[2 * lane + 1];
;       v2f sv[16];
; #pragma unroll
;       for (int i = 0; i < 16; ++i) sv[i] = *(const LAS v2f*)(SH + (16 * w + i) * 132 + 2 * lane);
;       float tr = 0.f, ti = 0.f;
; #pragma unroll
;       for (int i = 0; i < 16; ++i) { const float nr = a16r * tr - a16i * ti + sv[i][0], ni = a16r * ti + a16i * tr + sv[i][1]; tr = nr; ti = ni; }
	v_or_b32_e32 v82, 2, v7
	v_mov_b32_e32 v83, v111
	v_or_b32_e32 v84, 3, v7
	v_mov_b32_e32 v85, v111
	ds_write_b128 v3, v[100:103]
	ds_write_b128 v3, v[104:107] offset:400
	v_lshl_add_u64 v[78:79], v[138:139], 0, v[78:79]
	v_lshlrev_b64 v[80:81], 5, v[80:81]
	v_lshlrev_b64 v[82:83], 5, v[82:83]
	v_lshlrev_b64 v[84:85], 5, v[84:85]
	v_lshl_add_u64 v[80:81], v[138:139], 0, v[80:81]
	v_lshl_add_u64 v[82:83], v[138:139], 0, v[82:83]
	v_lshl_add_u64 v[84:85], v[138:139], 0, v[84:85]
	v_lshrrev_b32_e32 v244, 4, v162
	v_lshlrev_b32_e32 v244, 3, v244
	v_mov_b32_e32 v245, 0
	v_lshl_add_u64 v[78:79], v[78:79], 0, v[244:245]
	v_lshl_add_u64 v[82:83], v[82:83], 0, v[244:245]
	global_load_dwordx4 v[226:229], v[78:79], off nt
	global_load_dwordx4 v[230:233], v[82:83], off nt
	v_readlane_b32 s40, v249, 0
	s_and_b32 s40, s40, 63
	s_lshl_b32 s40, s40, 12
	v_and_b32_e32 v239, 15, v162
	v_lshrrev_b32_e32 v240, 4, v162
	v_lshlrev_b32_e32 v239, 8, v239
	v_lshl_add_u32 v239, v240, 4, v239
	v_add_u32_e32 v239, s40, v239
	global_load_dwordx4 v[58:61], v239, s[14:15]
	global_load_dwordx4 v[50:53], v239, s[14:15] offset:64
	global_load_dwordx4 v[62:65], v239, s[16:17]
	global_load_dwordx4 v[54:57], v239, s[16:17] offset:64
	global_load_dwordx4 v[42:45], v239, s[14:15] offset:128
	global_load_dwordx4 v[34:37], v239, s[14:15] offset:192
	global_load_dwordx4 v[46:49], v239, s[16:17] offset:128
	global_load_dwordx4 v[38:41], v239, s[16:17] offset:192
	s_lshl_b32 s41, s0, 11
	s_add_u32 s42, s20, s41
	s_addc_u32 s43, s21, 0
	v_and_b32_e32 v241, 15, v162
	v_lshlrev_b32_e32 v241, 2, v241
	v_lshl_or_b32 v241, v240, 9, v241
	global_load_dword v191, v241, s[42:43]
	global_load_dword v161, v241, s[42:43] offset:64
	global_load_dword v193, v241, s[42:43] offset:128
	global_load_dword v190, v241, s[42:43] offset:192
	global_load_dword v195, v241, s[42:43] offset:256
	global_load_dword v192, v241, s[42:43] offset:320
	global_load_dword v196, v241, s[42:43] offset:384
	global_load_dword v194, v241, s[42:43] offset:448
	s_lshl_b32 s41, s0, 6
	s_add_u32 s44, s18, s41
	s_addc_u32 s45, s19, 0
	s_lshl_b32 s41, s0, 7
	s_add_u32 s46, s22, s41
	s_addc_u32 s47, s23, 0
	v_lshlrev_b32_e32 v246, 4, v240
	global_load_dwordx4 v[18:21], v246, s[44:45]
	global_load_dwordx4 v[22:25], v246, s[46:47]
	global_load_dwordx4 v[26:29], v246, s[46:47] offset:64
	v_lshl_add_u64 v[78:79], s[6:7], 0, v[152:153]
	v_add_co_u32_e32 v80, vcc, s2, v78
	s_waitcnt lgkmcnt(0)
	s_mov_b32 s2, 0x2310000
	s_nop 0
	v_addc_co_u32_e32 v81, vcc, 0, v79, vcc
	v_add_co_u32_e32 v78, vcc, s2, v78
	v_add_u32_e32 v7, s8, v152
	s_nop 0
	v_addc_co_u32_e32 v79, vcc, 0, v79, vcc
	s_mul_i32 s4, s82, 0x2100
	v_add_u32_e32 v7, s4, v7
	v_add_u32_e32 v11, 0x800, v7
	ds_read2_b64 v[106:109], v7 offset1:66
	ds_read2_b64 v[102:105], v7 offset0:132 offset1:198
	ds_read2_b64 v[98:101], v11 offset0:8 offset1:74
	ds_read2_b64 v[94:97], v11 offset0:140 offset1:206
	v_add_u32_e32 v11, 0x1000, v7
	ds_read2_b64 v[90:93], v11 offset0:16 offset1:82
	ds_read2_b64 v[86:89], v11 offset0:148 offset1:214
	v_add_u32_e32 v11, 0x1800, v7
	ds_read2_b64 v[82:85], v11 offset0:24 offset1:90
	ds_read2_b64 v[78:81], v11 offset0:156 offset1:222
	s_lshl_b32 s4, s82, 9
	s_add_i32 s4, s4, 0
	s_mov_b32 s2, 0
	s_cmp_lt_u32 s84, 64
	s_waitcnt vmcnt(21)
	v_mov_b32_e32 v148, v234
	v_mov_b32_e32 v149, v235
	v_mov_b32_e32 v150, v236
	v_mov_b32_e32 v151, v237
	v_mul_f32_e32 v11, 0, v148
	v_mul_f32_e32 v155, 0, v149
	v_sub_f32_e32 v154, v11, v155
	v_fmac_f32_e32 v155, 0, v148
	s_waitcnt lgkmcnt(7)
	v_pk_add_f32 v[154:155], v[154:155], v[106:107]
	v_add_u32_e32 v11, s4, v152
	v_pk_mul_f32 v[156:157], v[148:149], v[154:155] op_sel:[1,1] op_sel_hi:[0,1]
	v_pk_fma_f32 v[158:159], v[148:149], v[154:155], v[156:157] op_sel_hi:[1,0,1]
	v_pk_fma_f32 v[156:157], v[148:149], v[154:155], v[156:157] op_sel_hi:[1,0,1] neg_lo:[0,0,1] neg_hi:[0,0,1]
	v_add_u32_e32 v11, 0x21000, v11
	v_mov_b32_e32 v157, v159
	v_pk_add_f32 v[156:157], v[108:109], v[156:157]
	v_mov_b32_e32 v152, v111
	v_pk_mul_f32 v[158:159], v[148:149], v[156:157] op_sel:[1,1] op_sel_hi:[0,1]
	v_pk_fma_f32 v[164:165], v[148:149], v[156:157], v[158:159] op_sel_hi:[1,0,1]
	v_pk_fma_f32 v[158:159], v[148:149], v[156:157], v[158:159] op_sel_hi:[1,0,1] neg_lo:[0,0,1] neg_hi:[0,0,1]
	s_nop 0
	v_mov_b32_e32 v159, v165
	s_waitcnt lgkmcnt(6)
	v_pk_add_f32 v[158:159], v[102:103], v[158:159]
	s_nop 0
	v_pk_mul_f32 v[164:165], v[148:149], v[158:159] op_sel:[1,1] op_sel_hi:[0,1]
	v_pk_fma_f32 v[166:167], v[148:149], v[158:159], v[164:165] op_sel_hi:[1,0,1]
	v_pk_fma_f32 v[164:165], v[148:149], v[158:159], v[164:165] op_sel_hi:[1,0,1] neg_lo:[0,0,1] neg_hi:[0,0,1]
	s_nop 0
	v_mov_b32_e32 v165, v167
	v_pk_add_f32 v[164:165], v[104:105], v[164:165]
	s_nop 0
	v_pk_mul_f32 v[166:167], v[148:149], v[164:165] op_sel:[1,1] op_sel_hi:[0,1]
	v_pk_fma_f32 v[168:169], v[148:149], v[164:165], v[166:167] op_sel_hi:[1,0,1]
	v_pk_fma_f32 v[166:167], v[148:149], v[164:165], v[166:167] op_sel_hi:[1,0,1] neg_lo:[0,0,1] neg_hi:[0,0,1]
	s_nop 0
	v_mov_b32_e32 v167, v169
	s_waitcnt lgkmcnt(5)
; #define LAS __attribute__((address_space(3)))
; __device__ __forceinline__ void s5_prompt_task(const Args& a, const Ctx& C, int b, int g, v4u (&xv)[8]) {
;     ...
;       v2f sv[16];
; #pragma unroll
;       for (int i = 0; i < 16; ++i) sv[i] = *(const LAS v2f*)(SH + (16 * w + i) * 132 + 2 * lane);
;       float tr = 0.f, ti = 0.f;
; #pragma unroll
;       for (int i = 0; i < 16; ++i) { const float nr = a16r * tr - a16i * ti + sv[i][0], ni = a16r * ti + a16i * tr + sv[i][1]; tr = nr; ti = ni; }
;       TW[w * 128 + 2 * lane] = tr; TW[w * 128 + 2 * lane + 1] = ti;
;       __syncthreads();
;       float hr = 0.f, hi = 0.f;
;       for (int v = 0; v < w; ++v) { const float sr = TW[v * 128 + 2 * lane], si = TW[v * 128 + 2 * lane + 1];
;           const float nr = a256r * hr - a256i * hi + sr, ni = a256r * hi + a256i * hr + si; hr = nr; hi = ni; }
	v_pk_add_f32 v[166:167], v[98:99], v[166:167]
	s_nop 0
	v_pk_mul_f32 v[168:169], v[148:149], v[166:167] op_sel:[1,1] op_sel_hi:[0,1]
	v_pk_fma_f32 v[170:171], v[148:149], v[166:167], v[168:169] op_sel_hi:[1,0,1]
	v_pk_fma_f32 v[168:169], v[148:149], v[166:167], v[168:169] op_sel_hi:[1,0,1] neg_lo:[0,0,1] neg_hi:[0,0,1]
	s_nop 0
	v_mov_b32_e32 v169, v171
	v_pk_add_f32 v[168:169], v[100:101], v[168:169]
	s_nop 0
	v_pk_mul_f32 v[170:171], v[148:149], v[168:169] op_sel:[1,1] op_sel_hi:[0,1]
	v_pk_fma_f32 v[172:173], v[148:149], v[168:169], v[170:171] op_sel_hi:[1,0,1]
	v_pk_fma_f32 v[170:171], v[148:149], v[168:169], v[170:171] op_sel_hi:[1,0,1] neg_lo:[0,0,1] neg_hi:[0,0,1]
	s_nop 0
	v_mov_b32_e32 v171, v173
	s_waitcnt lgkmcnt(4)
	v_pk_add_f32 v[170:171], v[94:95], v[170:171]
	s_nop 0
	v_pk_mul_f32 v[172:173], v[148:149], v[170:171] op_sel:[1,1] op_sel_hi:[0,1]
	v_pk_fma_f32 v[174:175], v[148:149], v[170:171], v[172:173] op_sel_hi:[1,0,1]
	v_pk_fma_f32 v[172:173], v[148:149], v[170:171], v[172:173] op_sel_hi:[1,0,1] neg_lo:[0,0,1] neg_hi:[0,0,1]
	s_nop 0
	v_mov_b32_e32 v173, v175
	v_pk_add_f32 v[172:173], v[96:97], v[172:173]
	s_nop 0
	v_pk_mul_f32 v[174:175], v[148:149], v[172:173] op_sel:[1,1] op_sel_hi:[0,1]
	v_pk_fma_f32 v[176:177], v[148:149], v[172:173], v[174:175] op_sel_hi:[1,0,1]
	v_pk_fma_f32 v[174:175], v[148:149], v[172:173], v[174:175] op_sel_hi:[1,0,1] neg_lo:[0,0,1] neg_hi:[0,0,1]
	s_nop 0
	v_mov_b32_e32 v175, v177
	s_waitcnt lgkmcnt(3)
	v_pk_add_f32 v[174:175], v[90:91], v[174:175]
	s_nop 0
	v_pk_mul_f32 v[176:177], v[148:149], v[174:175] op_sel:[1,1] op_sel_hi:[0,1]
	v_pk_fma_f32 v[178:179], v[148:149], v[174:175], v[176:177] op_sel_hi:[1,0,1]
	v_pk_fma_f32 v[176:177], v[148:149], v[174:175], v[176:177] op_sel_hi:[1,0,1] neg_lo:[0,0,1] neg_hi:[0,0,1]
	s_nop 0
	v_mov_b32_e32 v177, v179
	v_pk_add_f32 v[176:177], v[92:93], v[176:177]
	s_nop 0
	v_pk_mul_f32 v[178:179], v[148:149], v[176:177] op_sel:[1,1] op_sel_hi:[0,1]
	v_pk_fma_f32 v[180:181], v[148:149], v[176:177], v[178:179] op_sel_hi:[1,0,1]
	v_pk_fma_f32 v[178:179], v[148:149], v[176:177], v[178:179] op_sel_hi:[1,0,1] neg_lo:[0,0,1] neg_hi:[0,0,1]
	s_nop 0
	v_mov_b32_e32 v179, v181
	s_waitcnt lgkmcnt(2)
	v_pk_add_f32 v[178:179], v[86:87], v[178:179]
	s_nop 0
	v_pk_mul_f32 v[180:181], v[148:149], v[178:179] op_sel:[1,1] op_sel_hi:[0,1]
	v_pk_fma_f32 v[182:183], v[148:149], v[178:179], v[180:181] op_sel_hi:[1,0,1]
	v_pk_fma_f32 v[180:181], v[148:149], v[178:179], v[180:181] op_sel_hi:[1,0,1] neg_lo:[0,0,1] neg_hi:[0,0,1]
	s_nop 0
	v_mov_b32_e32 v181, v183
	v_pk_add_f32 v[182:183], v[88:89], v[180:181]
	s_nop 0
	v_pk_mul_f32 v[180:181], v[148:149], v[182:183] op_sel:[1,1] op_sel_hi:[0,1]
	v_pk_fma_f32 v[184:185], v[148:149], v[182:183], v[180:181] op_sel_hi:[1,0,1]
	v_pk_fma_f32 v[180:181], v[148:149], v[182:183], v[180:181] op_sel_hi:[1,0,1] neg_lo:[0,0,1] neg_hi:[0,0,1]
	s_nop 0
	v_mov_b32_e32 v181, v185
	s_waitcnt lgkmcnt(1)
	v_pk_add_f32 v[184:185], v[82:83], v[180:181]
	s_nop 0
	v_pk_mul_f32 v[180:181], v[148:149], v[184:185] op_sel:[1,1] op_sel_hi:[0,1]
	v_pk_fma_f32 v[186:187], v[148:149], v[184:185], v[180:181] op_sel_hi:[1,0,1]
	v_pk_fma_f32 v[180:181], v[148:149], v[184:185], v[180:181] op_sel_hi:[1,0,1] neg_lo:[0,0,1] neg_hi:[0,0,1]
	s_nop 0
	v_mov_b32_e32 v181, v187
	v_pk_add_f32 v[186:187], v[84:85], v[180:181]
	s_nop 0
	v_pk_mul_f32 v[180:181], v[148:149], v[186:187] op_sel:[1,1] op_sel_hi:[0,1]
	v_pk_fma_f32 v[188:189], v[148:149], v[186:187], v[180:181] op_sel_hi:[1,0,1]
	v_pk_fma_f32 v[180:181], v[148:149], v[186:187], v[180:181] op_sel_hi:[1,0,1] neg_lo:[0,0,1] neg_hi:[0,0,1]
	s_nop 0
	v_mov_b32_e32 v181, v189
	s_waitcnt lgkmcnt(0)
	v_pk_add_f32 v[188:189], v[78:79], v[180:181]
	s_nop 0
	v_pk_mul_f32 v[180:181], v[148:149], v[188:189] op_sel:[1,1] op_sel_hi:[0,1]
	v_pk_fma_f32 v[198:199], v[148:149], v[188:189], v[180:181] op_sel_hi:[1,0,1]
	v_pk_fma_f32 v[180:181], v[148:149], v[188:189], v[180:181] op_sel_hi:[1,0,1] neg_lo:[0,0,1] neg_hi:[0,0,1]
	s_nop 0
	v_mov_b32_e32 v181, v199
	v_pk_add_f32 v[180:181], v[80:81], v[180:181]
	ds_write_b64 v11, v[180:181]
	s_waitcnt lgkmcnt(0)
	s_barrier
	s_cbranch_scc1 .LBB0_985
	s_add_i32 s4, s82, -1
	s_cmp_lt_u32 s4, 7
	v_mov_b32_e32 v160, v111
	v_mov_b32_e32 v152, v111
	s_cbranch_scc1 .LBB0_977
	v_lshl_add_u32 v11, v162, 3, 0
	s_and_b32 s2, s82, 0x3fffff8
	s_waitcnt vmcnt(21)
	v_pk_mov_b32 v[154:155], v[150:151], v[150:151] op_sel:[1,0]
	s_mov_b32 s4, 0
	v_add_u32_e32 v11, 0x21000, v11
	v_mov_b32_e32 v152, 0
	v_mov_b32_e32 v160, 0

; __device__ __forceinline__ void s5_prompt_task(const Args& a, const Ctx& C, int b, int g, v4u (&xv)[8]) {
;     ...
;       float hr = 0.f, hi = 0.f;
;       for (int v = 0; v < w; ++v) { const float sr = TW[v * 128 + 2 * lane], si = TW[v * 128 + 2 * lane + 1];
;           const float nr = a256r * hr - a256i * hi + sr, ni = a256r * hi + a256i * hr + si; hr = nr; hi = ni; }
.LBB0_977:
	s_bfe_u32 s4, s84, 0x30006
	v_pk_mov_b32 v[180:181], v[148:149], v[148:149] op_sel:[1,0]
	s_cmp_eq_u32 s4, 0
	s_cbranch_scc1 .LBB0_983
	s_lshl_b32 s2, s2, 9
	s_add_i32 s2, s2, 0
	v_lshl_add_u32 v11, v162, 3, s2
	s_waitcnt vmcnt(21)
	v_pk_mov_b32 v[154:155], v[150:151], v[150:151] op_sel:[1,0]
	v_add_u32_e32 v11, 0x21000, v11
	v_mov_b32_e32 v153, v160

; #define LAS __attribute__((address_space(3)))
; __device__ __forceinline__ void s5_prompt_task(const Args& a, const Ctx& C, int b, int g, v4u (&xv)[8]) {
;     ...
; #pragma unroll
;       for (int i = 0; i < 16; ++i) { *(LAS v2f*)(SH + (16 * w + i) * 132 + 2 * lane) = (v2f){hr, hi};
;           const float nr = a16r * hr - a16i * hi + sv[i][0], ni = a16r * hi + a16i * hr + sv[i][1]; hr = nr; hi = ni; }
.LBB0_984:
	s_waitcnt vmcnt(21)
	v_pk_mul_f32 v[150:151], v[180:181], v[152:153] op_sel:[0,1]
	s_nop 0
	v_pk_fma_f32 v[154:155], v[148:149], v[152:153], v[150:151] op_sel_hi:[1,0,1]
	v_pk_fma_f32 v[150:151], v[148:149], v[152:153], v[150:151] op_sel_hi:[1,0,1] neg_lo:[0,0,1] neg_hi:[0,0,1]
	s_nop 0
	v_mov_b32_e32 v151, v155
	v_pk_add_f32 v[154:155], v[106:107], v[150:151]
	s_nop 0
	v_pk_mul_f32 v[106:107], v[180:181], v[154:155] op_sel:[0,1]
	s_nop 0
	v_pk_fma_f32 v[150:151], v[148:149], v[154:155], v[106:107] op_sel_hi:[1,0,1]
	v_pk_fma_f32 v[106:107], v[148:149], v[154:155], v[106:107] op_sel_hi:[1,0,1] neg_lo:[0,0,1] neg_hi:[0,0,1]
	s_nop 0
	v_mov_b32_e32 v107, v151
	v_pk_add_f32 v[156:157], v[108:109], v[106:107]
	s_nop 0
	v_pk_mul_f32 v[106:107], v[180:181], v[156:157] op_sel:[0,1]
	s_nop 0
	v_pk_fma_f32 v[108:109], v[148:149], v[156:157], v[106:107] op_sel_hi:[1,0,1]
	v_pk_fma_f32 v[106:107], v[148:149], v[156:157], v[106:107] op_sel_hi:[1,0,1] neg_lo:[0,0,1] neg_hi:[0,0,1]
	s_nop 0
	v_mov_b32_e32 v107, v109
	v_pk_add_f32 v[158:159], v[102:103], v[106:107]
	s_nop 0
	v_pk_mul_f32 v[102:103], v[180:181], v[158:159] op_sel:[0,1]
	s_nop 0
	v_pk_fma_f32 v[106:107], v[148:149], v[158:159], v[102:103] op_sel_hi:[1,0,1]
	v_pk_fma_f32 v[102:103], v[148:149], v[158:159], v[102:103] op_sel_hi:[1,0,1] neg_lo:[0,0,1] neg_hi:[0,0,1]
	s_nop 0
	v_mov_b32_e32 v103, v107
	v_pk_add_f32 v[164:165], v[104:105], v[102:103]
	s_nop 0
	v_pk_mul_f32 v[102:103], v[180:181], v[164:165] op_sel:[0,1]
	s_nop 0
	v_pk_fma_f32 v[104:105], v[148:149], v[164:165], v[102:103] op_sel_hi:[1,0,1]
	v_pk_fma_f32 v[102:103], v[148:149], v[164:165], v[102:103] op_sel_hi:[1,0,1] neg_lo:[0,0,1] neg_hi:[0,0,1]
	s_nop 0
	v_mov_b32_e32 v103, v105
	v_pk_add_f32 v[166:167], v[98:99], v[102:103]
	s_nop 0
	v_pk_mul_f32 v[98:99], v[180:181], v[166:167] op_sel:[0,1]
	s_nop 0
	v_pk_fma_f32 v[102:103], v[148:149], v[166:167], v[98:99] op_sel_hi:[1,0,1]
	v_pk_fma_f32 v[98:99], v[148:149], v[166:167], v[98:99] op_sel_hi:[1,0,1] neg_lo:[0,0,1] neg_hi:[0,0,1]
	s_nop 0
	v_mov_b32_e32 v99, v103
	v_pk_add_f32 v[168:169], v[100:101], v[98:99]
	s_nop 0
	v_pk_mul_f32 v[98:99], v[180:181], v[168:169] op_sel:[0,1]
	s_nop 0
	v_pk_fma_f32 v[100:101], v[148:149], v[168:169], v[98:99] op_sel_hi:[1,0,1]
	v_pk_fma_f32 v[98:99], v[148:149], v[168:169], v[98:99] op_sel_hi:[1,0,1] neg_lo:[0,0,1] neg_hi:[0,0,1]
	s_nop 0
	v_mov_b32_e32 v99, v101
	v_pk_add_f32 v[170:171], v[94:95], v[98:99]
	s_nop 0
	v_pk_mul_f32 v[94:95], v[180:181], v[170:171] op_sel:[0,1]
	s_nop 0
	v_pk_fma_f32 v[98:99], v[148:149], v[170:171], v[94:95] op_sel_hi:[1,0,1]
	v_pk_fma_f32 v[94:95], v[148:149], v[170:171], v[94:95] op_sel_hi:[1,0,1] neg_lo:[0,0,1] neg_hi:[0,0,1]
	s_nop 0
	v_mov_b32_e32 v95, v99
	v_pk_add_f32 v[172:173], v[96:97], v[94:95]
	s_nop 0
	v_pk_mul_f32 v[94:95], v[180:181], v[172:173] op_sel:[0,1]
	s_nop 0
	v_pk_fma_f32 v[96:97], v[148:149], v[172:173], v[94:95] op_sel_hi:[1,0,1]
	v_pk_fma_f32 v[94:95], v[148:149], v[172:173], v[94:95] op_sel_hi:[1,0,1] neg_lo:[0,0,1] neg_hi:[0,0,1]
	s_nop 0
	v_mov_b32_e32 v95, v97
	v_pk_add_f32 v[174:175], v[90:91], v[94:95]
	s_nop 0
	v_pk_mul_f32 v[90:91], v[180:181], v[174:175] op_sel:[0,1]
	s_nop 0
	v_pk_fma_f32 v[94:95], v[148:149], v[174:175], v[90:91] op_sel_hi:[1,0,1]
	v_pk_fma_f32 v[90:91], v[148:149], v[174:175], v[90:91] op_sel_hi:[1,0,1] neg_lo:[0,0,1] neg_hi:[0,0,1]
	s_nop 0
	v_mov_b32_e32 v91, v95
	v_pk_add_f32 v[176:177], v[92:93], v[90:91]
	s_nop 0
	v_pk_mul_f32 v[90:91], v[180:181], v[176:177] op_sel:[0,1]
	s_nop 0
	v_pk_fma_f32 v[92:93], v[148:149], v[176:177], v[90:91] op_sel_hi:[1,0,1]
	v_pk_fma_f32 v[90:91], v[148:149], v[176:177], v[90:91] op_sel_hi:[1,0,1] neg_lo:[0,0,1] neg_hi:[0,0,1]
	s_nop 0
	v_mov_b32_e32 v91, v93
	v_pk_add_f32 v[178:179], v[86:87], v[90:91]
	s_nop 0
	v_pk_mul_f32 v[86:87], v[180:181], v[178:179] op_sel:[0,1]
	s_nop 0
	v_pk_fma_f32 v[90:91], v[148:149], v[178:179], v[86:87] op_sel_hi:[1,0,1]
	v_pk_fma_f32 v[86:87], v[148:149], v[178:179], v[86:87] op_sel_hi:[1,0,1] neg_lo:[0,0,1] neg_hi:[0,0,1]
	s_nop 0
	v_mov_b32_e32 v87, v91
	v_pk_add_f32 v[182:183], v[88:89], v[86:87]
	s_nop 0
	v_pk_mul_f32 v[86:87], v[180:181], v[182:183] op_sel:[0,1]
	s_nop 0
	v_pk_fma_f32 v[88:89], v[148:149], v[182:183], v[86:87] op_sel_hi:[1,0,1]
	v_pk_fma_f32 v[86:87], v[148:149], v[182:183], v[86:87] op_sel_hi:[1,0,1] neg_lo:[0,0,1] neg_hi:[0,0,1]
	s_nop 0
	v_mov_b32_e32 v87, v89
	v_pk_add_f32 v[184:185], v[82:83], v[86:87]
	s_nop 0
	v_pk_mul_f32 v[82:83], v[180:181], v[184:185] op_sel:[0,1]
	s_nop 0
	v_pk_fma_f32 v[86:87], v[148:149], v[184:185], v[82:83] op_sel_hi:[1,0,1]
	v_pk_fma_f32 v[82:83], v[148:149], v[184:185], v[82:83] op_sel_hi:[1,0,1] neg_lo:[0,0,1] neg_hi:[0,0,1]
	s_nop 0
	v_mov_b32_e32 v83, v87
	v_pk_add_f32 v[186:187], v[84:85], v[82:83]
	s_nop 0
	v_pk_mul_f32 v[82:83], v[180:181], v[186:187] op_sel:[0,1]
	s_nop 0
	v_pk_fma_f32 v[84:85], v[148:149], v[186:187], v[82:83] op_sel_hi:[1,0,1]
	v_pk_fma_f32 v[82:83], v[148:149], v[186:187], v[82:83] op_sel_hi:[1,0,1] neg_lo:[0,0,1] neg_hi:[0,0,1]
	s_nop 0
	v_mov_b32_e32 v83, v85
	v_pk_add_f32 v[188:189], v[78:79], v[82:83]
	s_nop 0
	v_pk_mul_f32 v[78:79], v[180:181], v[188:189] op_sel:[0,1]
	s_nop 0
	v_pk_fma_f32 v[82:83], v[148:149], v[188:189], v[78:79] op_sel_hi:[1,0,1]
	v_pk_fma_f32 v[78:79], v[148:149], v[188:189], v[78:79] op_sel_hi:[1,0,1] neg_lo:[0,0,1] neg_hi:[0,0,1]
	s_nop 0
	v_mov_b32_e32 v79, v83
	v_pk_add_f32 v[180:181], v[80:81], v[78:79]

; #define LAS __attribute__((address_space(3)))
; __device__ __forceinline__ unsigned pk2(float lo, float hi) { return pg8::cvt_pk_bf16(lo, hi); }
; __device__ __forceinline__ bf16x8 pack8(f32x4 lo, f32x4 hi) { v4u w; w.x = pk2(lo[0], lo[1]); w.y = pk2(lo[2], lo[3]); w.z = pk2(hi[0], hi[1]); w.w = pk2(hi[2], hi[3]); return __builtin_bit_cast(bf16x8, w); }
; __device__ __forceinline__ void s5_load_consts(S5C& K, const Args& a, int g, int lane) {
;     ...
;     const float* cre = a.in[I_CRE] + ((size_t)g * 16 + fr) * 64; const float* cim = a.in[I_CIM] + ((size_t)g * 16 + fr) * 64;
; #pragma unroll
;     for (int j = 0; j < 4; ++j) { const f32x4 r4 = *(const f32x4*)(cre + 16 * j + 4 * q), i4 = *(const f32x4*)(cim + 16 * j + 4 * q); K.Cf[j] = pack8(r4, -i4); }
;     const float* wg = a.in[I_WGLU] + (size_t)g * 512;
;     { f32x4 v, gt;
; #pragma unroll
;       for (int e = 0; e < 4; ++e) { v[e] = wg[(4 * q + e) * 32 + fr]; gt[e] = wg[(4 * q + e) * 32 + 16 + fr]; }
;       K.Wv = (v2u){pk2(v[0], v[1]), pk2(v[2], v[3])}; K.Wg = (v2u){pk2(gt[0], gt[1]), pk2(gt[2], gt[3])}; }
; __device__ __forceinline__ void s5_prompt_task(const Args& a, const Ctx& C, int b, int g, v4u (&xv)[8]) {
;     ...
; #pragma unroll
;     for (int j = 0; j < 4; ++j) { const LAS float* s = SH + chunk * 132 + 2 * (16 * j + 4 * q); const f32x4 x0 = *(const LAS f32x4*)s, x1 = *(const LAS f32x4*)(s + 4);
;         hre[j] = (f32x4){x0[0], x0[2], x1[0], x1[2]}; him[j] = (f32x4){x0[1], x0[3], x1[1], x1[3]}; }
.LBB0_987:
	s_waitcnt vmcnt(0)
	v_xor_b32_e32 v15, 0x80000000, v63
	v_xor_b32_e32 v32, 0x80000000, v62
	v_xor_b32_e32 v7, 0x80000000, v65
	v_xor_b32_e32 v11, 0x80000000, v64
	v_cvt_pk_bf16_f32 v32, v32, v15
	v_xor_b32_e32 v15, 0x80000000, v55
	v_xor_b32_e32 v54, 0x80000000, v54
	v_cvt_pk_bf16_f32 v33, v11, v7
	v_xor_b32_e32 v7, 0x80000000, v57
	v_xor_b32_e32 v11, 0x80000000, v56
	v_cvt_pk_bf16_f32 v50, v50, v51
	v_cvt_pk_bf16_f32 v51, v52, v53
	v_cvt_pk_bf16_f32 v52, v54, v15
	v_xor_b32_e32 v15, 0x80000000, v47
	v_xor_b32_e32 v46, 0x80000000, v46
	v_cvt_pk_bf16_f32 v53, v11, v7
	v_xor_b32_e32 v7, 0x80000000, v49
	v_xor_b32_e32 v11, 0x80000000, v48
	v_cvt_pk_bf16_f32 v42, v42, v43
	v_cvt_pk_bf16_f32 v43, v44, v45
	v_cvt_pk_bf16_f32 v44, v46, v15
	v_xor_b32_e32 v15, 0x80000000, v39
	v_xor_b32_e32 v38, 0x80000000, v38
	s_waitcnt lgkmcnt(0)
	v_cvt_pk_bf16_f32 v30, v58, v59
	v_cvt_pk_bf16_f32 v31, v60, v61
	v_cvt_pk_bf16_f32 v45, v11, v7
	v_xor_b32_e32 v7, 0x80000000, v41
	v_xor_b32_e32 v11, 0x80000000, v40
	v_cvt_pk_bf16_f32 v34, v34, v35
	v_cvt_pk_bf16_f32 v35, v36, v37
	v_cvt_pk_bf16_f32 v36, v38, v15
	ds_read_b128 v[46:49], v3
	ds_read_b128 v[78:81], v3 offset:16
	ds_read_b128 v[54:57], v3 offset:128
	ds_read_b128 v[82:85], v3 offset:144
	ds_read_b128 v[38:41], v3 offset:256
	s_waitcnt vmcnt(21)
	ds_read_b128 v[148:151], v3 offset:272
	ds_read_b128 v[58:61], v3 offset:384
	ds_read_b128 v[152:155], v3 offset:400
	s_lshl_b64 s[4:5], s[70:71], 22
	v_lshlrev_b64 v[62:63], 11, v[110:111]
	v_lshl_add_u64 v[62:63], s[4:5], 0, v[62:63]
	v_or_b32_e32 v62, s1, v62
	v_lshl_add_u64 v[62:63], v[62:63], 0, v[112:113]
	v_lshl_add_u64 v[62:63], s[94:95], 0, v[62:63]
	s_mov_b64 s[0:1], 0x9801c00
	v_cvt_pk_bf16_f32 v37, v11, v7
	v_cvt_pk_bf16_f32 v102, v191, v193
	v_cvt_pk_bf16_f32 v103, v195, v196
	v_cvt_pk_bf16_f32 v104, v161, v190
	v_cvt_pk_bf16_f32 v105, v192, v194
	v_lshl_add_u64 v[106:107], v[62:63], 0, s[0:1]
	s_mov_b32 s0, 0
	s_mov_b32 s1, 0xc3e00000
	v_mov_b32_e32 v109, 0
	s_movk_i32 s2, 0xf000
	s_mov_b64 s[4:5], 0x2000
	v_mov_b32_e32 v111, 0x43e00000
	s_waitcnt lgkmcnt(7)
	v_mov_b32_e32 v62, v47
	v_mov_b32_e32 v63, v49
	s_waitcnt lgkmcnt(6)
	v_mov_b32_e32 v64, v79
	v_mov_b32_e32 v65, v81
	s_waitcnt lgkmcnt(5)
	v_mov_b32_e32 v66, v55
	v_mov_b32_e32 v67, v57
	s_waitcnt lgkmcnt(4)
	v_mov_b32_e32 v68, v83
	v_mov_b32_e32 v69, v85
	s_waitcnt lgkmcnt(3)
	v_mov_b32_e32 v70, v39
	v_mov_b32_e32 v71, v41
	s_waitcnt lgkmcnt(2)
	v_mov_b32_e32 v72, v149
	v_mov_b32_e32 v73, v151
	s_waitcnt lgkmcnt(1)
	v_mov_b32_e32 v74, v59
	v_mov_b32_e32 v75, v61
	s_waitcnt lgkmcnt(0)
	v_mov_b32_e32 v76, v153
	v_mov_b32_e32 v77, v155
	v_mov_b32_e32 v47, v48
	v_mov_b32_e32 v48, v78
	v_mov_b32_e32 v49, v80
	v_mov_b32_e32 v55, v56
	v_mov_b32_e32 v56, v82
	v_mov_b32_e32 v57, v84
	v_mov_b32_e32 v39, v40
	v_mov_b32_e32 v40, v148
	v_mov_b32_e32 v41, v150
	v_mov_b32_e32 v59, v60
	v_mov_b32_e32 v60, v152
	v_mov_b32_e32 v61, v154
